# GEMM mainloops: 32 leftover s_nop issue slots removed (every M0 write still has its wait state before the LDS-DMA)
# baseline (speedup 1.0000x reference)
; #define PG8_STAGE(bufoff, gbase, voff) do { _Pragma("unroll") for (int _i = 0; _i < 2; ++_i) \
;         __builtin_amdgcn_global_load_lds((const unsigned*)((const char*)(gbase) + (voff)[_i]), (LAS unsigned*)(lds + (bufoff) + ldsw + _i * 8192), 16, 0, 0); } while (0)
; #define PG8_LDA(dst, b, h) do { _Pragma("unroll") for (int m = 0; m < 4; ++m) _Pragma("unroll") for (int k = 0; k < 2; ++k) dst[m][k] = *(const LAS bf16x8*)(lds + PG8_SA(b, h) + aoff + m * 2048 + k * 1024); } while (0)
; #define PG8_LDB(dst, b, h) do { _Pragma("unroll") for (int n = 0; n < 2; ++n) _Pragma("unroll") for (int k = 0; k < 2; ++k) dst[n][k] = *(const LAS bf16x8*)(lds + PG8_SB(b, h) + boff + n * 2048 + k * 1024); } while (0)
; #define PG8_MMA(ai, bj, At, Bt) do { __builtin_amdgcn_s_setprio(1); _Pragma("unroll") for (int m = 0; m < 4; ++m) _Pragma("unroll") for (int n = 0; n < 2; ++n) _Pragma("unroll") for (int k = 0; k < 2; ++k) \
;         acc[ai][bj][m][n] = __builtin_amdgcn_mfma_f32_16x16x32_bf16(Bt[n][k], At[m][k], acc[ai][bj][m][n], 0, 0, 0); __builtin_amdgcn_s_setprio(0); } while (0)
; #define PG8_BAR __builtin_amdgcn_s_barrier()
; template <class Epi>
; __device__ __forceinline__ void gemm_phase(LAS unsigned char* lds, const Gemm g, const StaticOrder& S, const Epi& E, const int tid) {
;     ...
;         const char* nA = has_next ? (const char*)g.A + (size_t)nxt.pm * tstepA : cA; const char* nB = has_next ? (const char*)g.Bt + (size_t)nxt.pn * tstepB : cB;
;         for (int t = 0; t < nt; t += 2) {
;             const bool last = (t == nt - 2);
;             const char* a1 = cA + (size_t)(t + 1) * kstep + ((t + 1) >= 8 ? xtra : 0);
;             const char* a2 = last ? nA : cA + (size_t)(t + 2) * kstep + ((t + 2) >= 8 ? xtra : 0); const char* b2 = last ? nB : cB + (size_t)(t + 2) * kstep;
;             const char* a3 = a2 + kstep; const char* b3 = b2 + kstep;
;             PG8_LDB(B0, 0, 0); PG8_LDB(B1, 0, 1); PG8_SCHED; PG8_LDA(At, 0, 0); PG8_STAGE(PG8_SA(1, 1), a1 + hstepA, voffA);
;             PG8_WAIT_V(8); PG8_WAIT_L(0); PG8_BAR; PG8_MMA(0, 0, At, B0); PG8_MMA(0, 1, At, B1); PG8_BAR; PG8_SCHED;
;             PG8_LDA(At, 0, 1); PG8_STAGE(PG8_SB(0, 0), b2, voffB); PG8_STAGE(PG8_SB(0, 1), b2 + hstepB, voffB); PG8_STAGE(PG8_SA(0, 0), a2, voffA);
;             PG8_WAIT_V(8); PG8_WAIT_L(0); PG8_BAR; PG8_MMA(1, 0, At, B0); PG8_MMA(1, 1, At, B1); PG8_BAR; PG8_SCHED;
.LBB0_160:
	s_add_u32 s42, s94, 0x100
	s_addc_u32 s43, s95, 0
	s_add_i32 s8, 0, 0x10000
	v_add_u32_e32 v142, s8, v245
	v_add_u32_e32 v158, s15, v245
	ds_read_b128 v[122:125], v142
	ds_read_b128 v[126:129], v142 offset:1024
	ds_read_b128 v[138:141], v142 offset:2048
	ds_read_b128 v[142:145], v142 offset:3072
	ds_read_b128 v[146:149], v158
	ds_read_b128 v[150:153], v158 offset:1024
	ds_read_b128 v[154:157], v158 offset:2048
	ds_read_b128 v[158:161], v158 offset:3072
	s_cmp_eq_u32 s89, 12
	s_cselect_b32 vcc_hi, s91, s43
	s_cselect_b32 vcc_lo, s90, s42
	s_cselect_b32 s93, s36, s46
	s_cselect_b32 s92, s37, s45
	v_lshl_add_u64 v[210:211], s[94:95], 0, v[206:207]
	s_add_i32 m0, s19, 0xc000
	ds_read_b128 v[162:165], v246
	ds_read_b128 v[166:169], v246 offset:1024
	ds_read_b128 v[170:173], v246 offset:2048
	ds_read_b128 v[174:177], v246 offset:3072
	ds_read_b128 v[178:181], v246 offset:4096
	ds_read_b128 v[182:185], v246 offset:5120
	ds_read_b128 v[186:189], v246 offset:6144
	ds_read_b128 v[190:193], v246 offset:7168
	global_load_lds_dwordx4 v[210:211], off
	v_lshl_add_u64 v[210:211], s[94:95], 0, v[208:209]
	s_add_i32 m0, s19, 0xe000
	s_nop 0
	global_load_lds_dwordx4 v[210:211], off
	s_waitcnt vmcnt(8)
	s_waitcnt lgkmcnt(0)
	s_barrier
	s_setprio 1
	s_waitcnt lgkmcnt(0)
	v_mfma_f32_16x16x32_bf16 v[134:137], v[122:125], v[162:165], v[134:137]
	v_mfma_f32_16x16x32_bf16 v[130:133], v[138:141], v[162:165], v[130:133]
	v_mfma_f32_16x16x32_bf16 v[108:111], v[122:125], v[170:173], v[108:111]
	v_mfma_f32_16x16x32_bf16 v[104:107], v[138:141], v[170:173], v[104:107]
	v_mfma_f32_16x16x32_bf16 v[92:95], v[122:125], v[178:181], v[92:95]
	v_mfma_f32_16x16x32_bf16 v[88:91], v[138:141], v[178:181], v[88:91]
	v_mfma_f32_16x16x32_bf16 v[76:79], v[122:125], v[186:189], v[76:79]
	v_mfma_f32_16x16x32_bf16 v[72:75], v[138:141], v[186:189], v[72:75]
	v_mfma_f32_16x16x32_bf16 v[134:137], v[126:129], v[166:169], v[134:137]
	v_mfma_f32_16x16x32_bf16 v[130:133], v[142:145], v[166:169], v[130:133]
	v_mfma_f32_16x16x32_bf16 v[108:111], v[126:129], v[174:177], v[108:111]
	v_mfma_f32_16x16x32_bf16 v[104:107], v[142:145], v[174:177], v[104:107]
	v_mfma_f32_16x16x32_bf16 v[92:95], v[126:129], v[182:185], v[92:95]
	v_mfma_f32_16x16x32_bf16 v[88:91], v[142:145], v[182:185], v[88:91]
	v_mfma_f32_16x16x32_bf16 v[76:79], v[126:129], v[190:193], v[76:79]
	v_mfma_f32_16x16x32_bf16 v[72:75], v[142:145], v[190:193], v[72:75]
	v_mfma_f32_16x16x32_bf16 v[118:121], v[146:149], v[162:165], v[118:121]
	v_mfma_f32_16x16x32_bf16 v[114:117], v[154:157], v[162:165], v[114:117]
	v_mfma_f32_16x16x32_bf16 v[100:103], v[146:149], v[170:173], v[100:103]
	v_mfma_f32_16x16x32_bf16 v[96:99], v[154:157], v[170:173], v[96:99]
	v_mfma_f32_16x16x32_bf16 v[84:87], v[146:149], v[178:181], v[84:87]
	v_mfma_f32_16x16x32_bf16 v[80:83], v[154:157], v[178:181], v[80:83]
	v_mfma_f32_16x16x32_bf16 v[68:71], v[146:149], v[186:189], v[68:71]
	v_mfma_f32_16x16x32_bf16 v[64:67], v[154:157], v[186:189], v[64:67]
	v_mfma_f32_16x16x32_bf16 v[118:121], v[150:153], v[166:169], v[118:121]
	v_mfma_f32_16x16x32_bf16 v[114:117], v[158:161], v[166:169], v[114:117]
	v_mfma_f32_16x16x32_bf16 v[100:103], v[150:153], v[174:177], v[100:103]
	v_mfma_f32_16x16x32_bf16 v[96:99], v[158:161], v[174:177], v[96:99]
	v_mfma_f32_16x16x32_bf16 v[84:87], v[150:153], v[182:185], v[84:87]
	v_mfma_f32_16x16x32_bf16 v[80:83], v[158:161], v[182:185], v[80:83]
	v_mfma_f32_16x16x32_bf16 v[68:71], v[150:153], v[190:193], v[68:71]
	v_mfma_f32_16x16x32_bf16 v[64:67], v[158:161], v[190:193], v[64:67]
	s_setprio 0
	s_barrier
	s_add_i32 s8, s8, s11
	v_lshl_add_u64 v[210:211], s[92:93], 0, v[112:113]
	s_mov_b32 m0, s8
	ds_read_b128 v[162:165], v246 offset:16384
	ds_read_b128 v[166:169], v246 offset:17408
	ds_read_b128 v[170:173], v246 offset:18432
	ds_read_b128 v[174:177], v246 offset:19456
	ds_read_b128 v[178:181], v246 offset:20480
	ds_read_b128 v[182:185], v246 offset:21504
	ds_read_b128 v[186:189], v246 offset:22528
	ds_read_b128 v[190:193], v246 offset:23552
	global_load_lds_dwordx4 v112, s[92:93]
	s_add_i32 m0, s8, 0x2000
	s_add_u32 s8, s92, 0x40000
	v_lshl_add_u64 v[212:213], s[92:93], 0, v[200:201]
	s_addc_u32 s9, s93, 0
	s_add_i32 s13, s15, s11
	global_load_lds_dwordx4 v200, s[92:93]
	s_mov_b32 m0, s13
	s_nop 0
	global_load_lds_dwordx4 v112, s[8:9]
	s_add_i32 m0, s13, 0x2000
	s_nop 0
	global_load_lds_dwordx4 v200, s[8:9]
	s_mov_b32 m0, s19
	s_nop 0
	global_load_lds_dwordx4 v202, vcc
	s_mov_b32 m0, s28
	s_nop 0
	global_load_lds_dwordx4 v204, vcc
	s_waitcnt vmcnt(8)
	s_waitcnt lgkmcnt(0)
	s_barrier
; #define PG8_STAGE(bufoff, gbase, voff) do { _Pragma("unroll") for (int _i = 0; _i < 2; ++_i) \
;         __builtin_amdgcn_global_load_lds((const unsigned*)((const char*)(gbase) + (voff)[_i]), (LAS unsigned*)(lds + (bufoff) + ldsw + _i * 8192), 16, 0, 0); } while (0)
; #define PG8_LDA(dst, b, h) do { _Pragma("unroll") for (int m = 0; m < 4; ++m) _Pragma("unroll") for (int k = 0; k < 2; ++k) dst[m][k] = *(const LAS bf16x8*)(lds + PG8_SA(b, h) + aoff + m * 2048 + k * 1024); } while (0)
; #define PG8_LDB(dst, b, h) do { _Pragma("unroll") for (int n = 0; n < 2; ++n) _Pragma("unroll") for (int k = 0; k < 2; ++k) dst[n][k] = *(const LAS bf16x8*)(lds + PG8_SB(b, h) + boff + n * 2048 + k * 1024); } while (0)
; #define PG8_MMA(ai, bj, At, Bt) do { __builtin_amdgcn_s_setprio(1); _Pragma("unroll") for (int m = 0; m < 4; ++m) _Pragma("unroll") for (int n = 0; n < 2; ++n) _Pragma("unroll") for (int k = 0; k < 2; ++k) \
;         acc[ai][bj][m][n] = __builtin_amdgcn_mfma_f32_16x16x32_bf16(Bt[n][k], At[m][k], acc[ai][bj][m][n], 0, 0, 0); __builtin_amdgcn_s_setprio(0); } while (0)
; #define PG8_WAIT_V(n) asm volatile("s_waitcnt vmcnt(" #n ")" ::: "memory")
; #define PG8_WAIT_L(n) asm volatile("s_waitcnt lgkmcnt(" #n ")" ::: "memory")
; #define PG8_BAR __builtin_amdgcn_s_barrier()
; #define PG8_SCHED __builtin_amdgcn_sched_barrier(0)
; template <class Epi>
; __device__ __forceinline__ void gemm_phase(LAS unsigned char* lds, const Gemm g, const StaticOrder& S, const Epi& E, const int tid) {
;     ...
;             PG8_WAIT_V(8); PG8_WAIT_L(0); PG8_BAR; PG8_MMA(1, 0, At, B0); PG8_MMA(1, 1, At, B1); PG8_BAR; PG8_SCHED;
;             PG8_LDB(B0, 1, 0); PG8_LDB(B1, 1, 1); PG8_SCHED; PG8_LDA(At, 1, 0); PG8_STAGE(PG8_SA(0, 1), a2 + hstepA, voffA);
;             PG8_WAIT_V(8); PG8_WAIT_L(0); PG8_BAR; PG8_MMA(0, 0, At, B0); PG8_MMA(0, 1, At, B1); PG8_BAR; PG8_SCHED;
	s_setprio 1
	s_waitcnt lgkmcnt(0)
	v_mfma_f32_16x16x32_bf16 v[60:63], v[122:125], v[162:165], v[60:63]
	v_mfma_f32_16x16x32_bf16 v[56:59], v[138:141], v[162:165], v[56:59]
	v_mfma_f32_16x16x32_bf16 v[44:47], v[122:125], v[170:173], v[44:47]
	v_mfma_f32_16x16x32_bf16 v[40:43], v[138:141], v[170:173], v[40:43]
	v_mfma_f32_16x16x32_bf16 v[28:31], v[122:125], v[178:181], v[28:31]
	v_mfma_f32_16x16x32_bf16 v[24:27], v[138:141], v[178:181], v[24:27]
	v_mfma_f32_16x16x32_bf16 v[12:15], v[122:125], v[186:189], v[12:15]
	v_mfma_f32_16x16x32_bf16 v[8:11], v[138:141], v[186:189], v[8:11]
	v_mfma_f32_16x16x32_bf16 v[60:63], v[126:129], v[166:169], v[60:63]
	v_mfma_f32_16x16x32_bf16 v[56:59], v[142:145], v[166:169], v[56:59]
	v_mfma_f32_16x16x32_bf16 v[44:47], v[126:129], v[174:177], v[44:47]
	v_mfma_f32_16x16x32_bf16 v[40:43], v[142:145], v[174:177], v[40:43]
	v_mfma_f32_16x16x32_bf16 v[28:31], v[126:129], v[182:185], v[28:31]
	v_mfma_f32_16x16x32_bf16 v[24:27], v[142:145], v[182:185], v[24:27]
	v_mfma_f32_16x16x32_bf16 v[12:15], v[126:129], v[190:193], v[12:15]
	v_mfma_f32_16x16x32_bf16 v[8:11], v[142:145], v[190:193], v[8:11]
	v_mfma_f32_16x16x32_bf16 v[52:55], v[146:149], v[162:165], v[52:55]
	v_mfma_f32_16x16x32_bf16 v[48:51], v[154:157], v[162:165], v[48:51]
	v_mfma_f32_16x16x32_bf16 v[36:39], v[146:149], v[170:173], v[36:39]
	v_mfma_f32_16x16x32_bf16 v[32:35], v[154:157], v[170:173], v[32:35]
	v_mfma_f32_16x16x32_bf16 v[20:23], v[146:149], v[178:181], v[20:23]
	v_mfma_f32_16x16x32_bf16 v[16:19], v[154:157], v[178:181], v[16:19]
	v_mfma_f32_16x16x32_bf16 v[4:7], v[146:149], v[186:189], v[4:7]
	v_mfma_f32_16x16x32_bf16 v[0:3], v[154:157], v[186:189], v[0:3]
	v_mfma_f32_16x16x32_bf16 v[52:55], v[150:153], v[166:169], v[52:55]
	v_mfma_f32_16x16x32_bf16 v[48:51], v[158:161], v[166:169], v[48:51]
	v_mfma_f32_16x16x32_bf16 v[36:39], v[150:153], v[174:177], v[36:39]
	v_mfma_f32_16x16x32_bf16 v[32:35], v[158:161], v[174:177], v[32:35]
	v_mfma_f32_16x16x32_bf16 v[20:23], v[150:153], v[182:185], v[20:23]
	v_mfma_f32_16x16x32_bf16 v[16:19], v[158:161], v[182:185], v[16:19]
	v_mfma_f32_16x16x32_bf16 v[4:7], v[150:153], v[190:193], v[4:7]
	v_mfma_f32_16x16x32_bf16 v[0:3], v[158:161], v[190:193], v[0:3]
	s_setprio 0
	s_barrier
	s_add_i32 s13, 0, 0x18000
	s_add_i32 s31, 0, 0x1c000
	v_add_u32_e32 v142, s13, v245
	v_add_u32_e32 v158, s31, v245
	ds_read_b128 v[122:125], v142
	ds_read_b128 v[126:129], v142 offset:1024
	ds_read_b128 v[138:141], v142 offset:2048
	ds_read_b128 v[142:145], v142 offset:3072
	ds_read_b128 v[146:149], v158
	ds_read_b128 v[150:153], v158 offset:1024
	ds_read_b128 v[154:157], v158 offset:2048
	ds_read_b128 v[158:161], v158 offset:3072
	s_add_u32 s8, vcc_lo, 0xc0000
	s_addc_u32 s9, vcc_hi, 0
	s_mov_b32 m0, s30
	ds_read_b128 v[162:165], v246 offset:32768
	ds_read_b128 v[166:169], v246 offset:33792
	ds_read_b128 v[170:173], v246 offset:34816
	ds_read_b128 v[174:177], v246 offset:35840
	ds_read_b128 v[178:181], v246 offset:36864
	ds_read_b128 v[182:185], v246 offset:37888
	ds_read_b128 v[186:189], v246 offset:38912
	ds_read_b128 v[190:193], v246 offset:39936
	global_load_lds_dwordx4 v202, s[8:9]
	v_lshl_add_u64 v[248:249], s[8:9], 0, v[204:205]
	s_mov_b32 m0, s35
	s_nop 0
	global_load_lds_dwordx4 v204, s[8:9]
	s_waitcnt vmcnt(8)
	s_waitcnt lgkmcnt(0)
	s_barrier
	s_setprio 1
	s_waitcnt lgkmcnt(0)
	v_mfma_f32_16x16x32_bf16 v[134:137], v[122:125], v[162:165], v[134:137]
	v_mfma_f32_16x16x32_bf16 v[130:133], v[138:141], v[162:165], v[130:133]
	v_mfma_f32_16x16x32_bf16 v[108:111], v[122:125], v[170:173], v[108:111]
	v_mfma_f32_16x16x32_bf16 v[104:107], v[138:141], v[170:173], v[104:107]
	v_mfma_f32_16x16x32_bf16 v[92:95], v[122:125], v[178:181], v[92:95]
	v_mfma_f32_16x16x32_bf16 v[88:91], v[138:141], v[178:181], v[88:91]
	v_mfma_f32_16x16x32_bf16 v[76:79], v[122:125], v[186:189], v[76:79]
	v_mfma_f32_16x16x32_bf16 v[72:75], v[138:141], v[186:189], v[72:75]
	v_mfma_f32_16x16x32_bf16 v[134:137], v[126:129], v[166:169], v[134:137]
	v_mfma_f32_16x16x32_bf16 v[130:133], v[142:145], v[166:169], v[130:133]
	v_mfma_f32_16x16x32_bf16 v[108:111], v[126:129], v[174:177], v[108:111]
	v_mfma_f32_16x16x32_bf16 v[104:107], v[142:145], v[174:177], v[104:107]
	v_mfma_f32_16x16x32_bf16 v[92:95], v[126:129], v[182:185], v[92:95]
	v_mfma_f32_16x16x32_bf16 v[88:91], v[142:145], v[182:185], v[88:91]
	v_mfma_f32_16x16x32_bf16 v[76:79], v[126:129], v[190:193], v[76:79]
	v_mfma_f32_16x16x32_bf16 v[72:75], v[142:145], v[190:193], v[72:75]
	v_mfma_f32_16x16x32_bf16 v[118:121], v[146:149], v[162:165], v[118:121]
	v_mfma_f32_16x16x32_bf16 v[114:117], v[154:157], v[162:165], v[114:117]
	v_mfma_f32_16x16x32_bf16 v[100:103], v[146:149], v[170:173], v[100:103]
	v_mfma_f32_16x16x32_bf16 v[96:99], v[154:157], v[170:173], v[96:99]
	v_mfma_f32_16x16x32_bf16 v[84:87], v[146:149], v[178:181], v[84:87]
	v_mfma_f32_16x16x32_bf16 v[80:83], v[154:157], v[178:181], v[80:83]
	v_mfma_f32_16x16x32_bf16 v[68:71], v[146:149], v[186:189], v[68:71]
	v_mfma_f32_16x16x32_bf16 v[64:67], v[154:157], v[186:189], v[64:67]
	v_mfma_f32_16x16x32_bf16 v[118:121], v[150:153], v[166:169], v[118:121]
	v_mfma_f32_16x16x32_bf16 v[114:117], v[158:161], v[166:169], v[114:117]
	v_mfma_f32_16x16x32_bf16 v[100:103], v[150:153], v[174:177], v[100:103]
	v_mfma_f32_16x16x32_bf16 v[96:99], v[158:161], v[174:177], v[96:99]
	v_mfma_f32_16x16x32_bf16 v[84:87], v[150:153], v[182:185], v[84:87]
	v_mfma_f32_16x16x32_bf16 v[80:83], v[158:161], v[182:185], v[80:83]
	v_mfma_f32_16x16x32_bf16 v[68:71], v[150:153], v[190:193], v[68:71]
	v_mfma_f32_16x16x32_bf16 v[64:67], v[158:161], v[190:193], v[64:67]
	s_setprio 0
	s_barrier
; #define PG8_STAGE(bufoff, gbase, voff) do { _Pragma("unroll") for (int _i = 0; _i < 2; ++_i) \
;         __builtin_amdgcn_global_load_lds((const unsigned*)((const char*)(gbase) + (voff)[_i]), (LAS unsigned*)(lds + (bufoff) + ldsw + _i * 8192), 16, 0, 0); } while (0)
; #define PG8_LDA(dst, b, h) do { _Pragma("unroll") for (int m = 0; m < 4; ++m) _Pragma("unroll") for (int k = 0; k < 2; ++k) dst[m][k] = *(const LAS bf16x8*)(lds + PG8_SA(b, h) + aoff + m * 2048 + k * 1024); } while (0)
; #define PG8_MMA(ai, bj, At, Bt) do { __builtin_amdgcn_s_setprio(1); _Pragma("unroll") for (int m = 0; m < 4; ++m) _Pragma("unroll") for (int n = 0; n < 2; ++n) _Pragma("unroll") for (int k = 0; k < 2; ++k) \
;         acc[ai][bj][m][n] = __builtin_amdgcn_mfma_f32_16x16x32_bf16(Bt[n][k], At[m][k], acc[ai][bj][m][n], 0, 0, 0); __builtin_amdgcn_s_setprio(0); } while (0)
; #define PG8_WAIT_V(n) asm volatile("s_waitcnt vmcnt(" #n ")" ::: "memory")
; #define PG8_WAIT_L(n) asm volatile("s_waitcnt lgkmcnt(" #n ")" ::: "memory")
; #define PG8_BAR __builtin_amdgcn_s_barrier()
; #define PG8_SCHED __builtin_amdgcn_sched_barrier(0)
; template <class Epi>
; __device__ __forceinline__ void gemm_phase(LAS unsigned char* lds, const Gemm g, const StaticOrder& S, const Epi& E, const int tid) {
;     ...
;             PG8_LDA(At, 1, 1); PG8_STAGE(PG8_SB(1, 0), b3, voffB); PG8_STAGE(PG8_SB(1, 1), b3 + hstepB, voffB); PG8_STAGE(PG8_SA(1, 0), a3, voffA);
;             PG8_WAIT_V(8); PG8_WAIT_L(0); PG8_BAR; PG8_MMA(1, 0, At, B0); PG8_MMA(1, 1, At, B1); PG8_BAR; PG8_SCHED;
;         }
;         if (wr == 0) PG8_BAR;
	s_add_i32 s8, s13, s11
	s_add_u32 s100, s92, 0x80
	s_addc_u32 s101, s93, 0
	s_mov_b32 m0, s8
	ds_read_b128 v[162:165], v246 offset:49152
	ds_read_b128 v[166:169], v246 offset:50176
	ds_read_b128 v[170:173], v246 offset:51200
	ds_read_b128 v[174:177], v246 offset:52224
	ds_read_b128 v[178:181], v246 offset:53248
	ds_read_b128 v[182:185], v246 offset:54272
	ds_read_b128 v[186:189], v246 offset:55296
	ds_read_b128 v[190:193], v246 offset:56320
	global_load_lds_dwordx4 v112, s[100:101]
	s_add_i32 m0, s8, 0x2000
	s_add_u32 s8, s92, 0x40080
	v_lshl_add_u64 v[210:211], v[212:213], 0, s[24:25]
	s_addc_u32 s9, s93, 0
	s_add_i32 s13, s31, s11
	global_load_lds_dwordx4 v[210:211], off
	s_mov_b32 m0, s13
	s_nop 0
	global_load_lds_dwordx4 v112, s[8:9]
	s_add_i32 m0, s13, 0x2000
	s_nop 0
	global_load_lds_dwordx4 v200, s[8:9]
	s_add_u32 s100, vcc_lo, 0x80
	s_addc_u32 s101, vcc_hi, 0
	s_mov_b32 m0, s38
	s_nop 0
	global_load_lds_dwordx4 v202, s[100:101]
	s_add_u32 s100, vcc_lo, 0x80
	s_addc_u32 s101, vcc_hi, 0
	s_mov_b32 m0, s39
	s_nop 0
	global_load_lds_dwordx4 v204, s[100:101]
	s_waitcnt vmcnt(8)
	s_waitcnt lgkmcnt(0)
	s_barrier
	s_setprio 1
	s_waitcnt lgkmcnt(0)
	v_mfma_f32_16x16x32_bf16 v[60:63], v[122:125], v[162:165], v[60:63]
	v_mfma_f32_16x16x32_bf16 v[56:59], v[138:141], v[162:165], v[56:59]
	v_mfma_f32_16x16x32_bf16 v[44:47], v[122:125], v[170:173], v[44:47]
	v_mfma_f32_16x16x32_bf16 v[40:43], v[138:141], v[170:173], v[40:43]
	v_mfma_f32_16x16x32_bf16 v[28:31], v[122:125], v[178:181], v[28:31]
	v_mfma_f32_16x16x32_bf16 v[24:27], v[138:141], v[178:181], v[24:27]
	v_mfma_f32_16x16x32_bf16 v[12:15], v[122:125], v[186:189], v[12:15]
	v_mfma_f32_16x16x32_bf16 v[8:11], v[138:141], v[186:189], v[8:11]
	v_mfma_f32_16x16x32_bf16 v[60:63], v[126:129], v[166:169], v[60:63]
	v_mfma_f32_16x16x32_bf16 v[56:59], v[142:145], v[166:169], v[56:59]
	v_mfma_f32_16x16x32_bf16 v[44:47], v[126:129], v[174:177], v[44:47]
	v_mfma_f32_16x16x32_bf16 v[40:43], v[142:145], v[174:177], v[40:43]
	v_mfma_f32_16x16x32_bf16 v[28:31], v[126:129], v[182:185], v[28:31]
	v_mfma_f32_16x16x32_bf16 v[24:27], v[142:145], v[182:185], v[24:27]
	v_mfma_f32_16x16x32_bf16 v[12:15], v[126:129], v[190:193], v[12:15]
	v_mfma_f32_16x16x32_bf16 v[8:11], v[142:145], v[190:193], v[8:11]
	v_mfma_f32_16x16x32_bf16 v[52:55], v[146:149], v[162:165], v[52:55]
	v_mfma_f32_16x16x32_bf16 v[48:51], v[154:157], v[162:165], v[48:51]
	v_mfma_f32_16x16x32_bf16 v[36:39], v[146:149], v[170:173], v[36:39]
	v_mfma_f32_16x16x32_bf16 v[32:35], v[154:157], v[170:173], v[32:35]
	v_mfma_f32_16x16x32_bf16 v[20:23], v[146:149], v[178:181], v[20:23]
	v_mfma_f32_16x16x32_bf16 v[16:19], v[154:157], v[178:181], v[16:19]
	v_mfma_f32_16x16x32_bf16 v[4:7], v[146:149], v[186:189], v[4:7]
	v_mfma_f32_16x16x32_bf16 v[0:3], v[154:157], v[186:189], v[0:3]
	v_mfma_f32_16x16x32_bf16 v[52:55], v[150:153], v[166:169], v[52:55]
	v_mfma_f32_16x16x32_bf16 v[48:51], v[158:161], v[166:169], v[48:51]
	v_mfma_f32_16x16x32_bf16 v[36:39], v[150:153], v[174:177], v[36:39]
	v_mfma_f32_16x16x32_bf16 v[32:35], v[158:161], v[174:177], v[32:35]
	v_mfma_f32_16x16x32_bf16 v[20:23], v[150:153], v[182:185], v[20:23]
	v_mfma_f32_16x16x32_bf16 v[16:19], v[158:161], v[182:185], v[16:19]
	v_mfma_f32_16x16x32_bf16 v[4:7], v[150:153], v[190:193], v[4:7]
	v_mfma_f32_16x16x32_bf16 v[0:3], v[158:161], v[190:193], v[0:3]
	s_setprio 0
	s_barrier
	s_add_i32 s89, s89, 2
	s_add_u32 s45, s45, 0x100
	s_addc_u32 s46, s46, 0
	s_cmp_gt_u32 s89, 13
	s_mov_b64 s[94:95], s[42:43]
	s_cbranch_scc0 .LBB0_160
	s_and_b64 vcc, exec, s[86:87]
	s_cbranch_vccz .LBB0_163
	s_barrier

; #define PG8_STAGE(bufoff, gbase, voff) do { _Pragma("unroll") for (int _i = 0; _i < 2; ++_i) \
;         __builtin_amdgcn_global_load_lds((const unsigned*)((const char*)(gbase) + (voff)[_i]), (LAS unsigned*)(lds + (bufoff) + ldsw + _i * 8192), 16, 0, 0); } while (0)
; #define PG8_LDA(dst, b, h) do { _Pragma("unroll") for (int m = 0; m < 4; ++m) _Pragma("unroll") for (int k = 0; k < 2; ++k) dst[m][k] = *(const LAS bf16x8*)(lds + PG8_SA(b, h) + aoff + m * 2048 + k * 1024); } while (0)
; #define PG8_LDB(dst, b, h) do { _Pragma("unroll") for (int n = 0; n < 2; ++n) _Pragma("unroll") for (int k = 0; k < 2; ++k) dst[n][k] = *(const LAS bf16x8*)(lds + PG8_SB(b, h) + boff + n * 2048 + k * 1024); } while (0)
; #define PG8_MMA(ai, bj, At, Bt) do { __builtin_amdgcn_s_setprio(1); _Pragma("unroll") for (int m = 0; m < 4; ++m) _Pragma("unroll") for (int n = 0; n < 2; ++n) _Pragma("unroll") for (int k = 0; k < 2; ++k) \
;         acc[ai][bj][m][n] = __builtin_amdgcn_mfma_f32_16x16x32_bf16(Bt[n][k], At[m][k], acc[ai][bj][m][n], 0, 0, 0); __builtin_amdgcn_s_setprio(0); } while (0)
; #define PG8_BAR __builtin_amdgcn_s_barrier()
; template <class Epi>
; __device__ __forceinline__ void gemm_phase(LAS unsigned char* lds, const Gemm g, const StaticOrder& S, const Epi& E, const int tid) {
;     ...
;         const char* nA = has_next ? (const char*)g.A + (size_t)nxt.pm * tstepA : cA; const char* nB = has_next ? (const char*)g.Bt + (size_t)nxt.pn * tstepB : cB;
;         for (int t = 0; t < nt; t += 2) {
;             const bool last = (t == nt - 2);
;             const char* a1 = cA + (size_t)(t + 1) * kstep + ((t + 1) >= 8 ? xtra : 0);
;             const char* a2 = last ? nA : cA + (size_t)(t + 2) * kstep + ((t + 2) >= 8 ? xtra : 0); const char* b2 = last ? nB : cB + (size_t)(t + 2) * kstep;
;             const char* a3 = a2 + kstep; const char* b3 = b2 + kstep;
;             PG8_LDB(B0, 0, 0); PG8_LDB(B1, 0, 1); PG8_SCHED; PG8_LDA(At, 0, 0); PG8_STAGE(PG8_SA(1, 1), a1 + hstepA, voffA);
;             PG8_WAIT_V(8); PG8_WAIT_L(0); PG8_BAR; PG8_MMA(0, 0, At, B0); PG8_MMA(0, 1, At, B1); PG8_BAR; PG8_SCHED;
;             PG8_LDA(At, 0, 1); PG8_STAGE(PG8_SB(0, 0), b2, voffB); PG8_STAGE(PG8_SB(0, 1), b2 + hstepB, voffB); PG8_STAGE(PG8_SA(0, 0), a2, voffA);
;             PG8_WAIT_V(8); PG8_WAIT_L(0); PG8_BAR; PG8_MMA(1, 0, At, B0); PG8_MMA(1, 1, At, B1); PG8_BAR; PG8_SCHED;
.LBB0_230:
	s_add_i32 s96, s40, 2
	s_cmp_gt_u32 s96, 7
	s_cselect_b32 s46, 0x600, 0
	s_cmp_gt_u32 s96, 5
	s_cselect_b32 s8, 0x600, 0
	s_add_u32 s8, s88, s8
	s_addc_u32 s9, s89, 0
	s_add_u32 s8, s8, 0x100
	s_addc_u32 s9, s9, 0
	s_add_i32 s13, 0, 0x10000
	v_add_u32_e32 v142, s13, v210
	v_add_u32_e32 v158, s15, v210
	ds_read_b128 v[130:133], v142
	ds_read_b128 v[134:137], v142 offset:1024
	ds_read_b128 v[138:141], v142 offset:2048
	ds_read_b128 v[142:145], v142 offset:3072
	ds_read_b128 v[146:149], v158
	ds_read_b128 v[150:153], v158 offset:1024
	ds_read_b128 v[154:157], v158 offset:2048
	ds_read_b128 v[158:161], v158 offset:3072
	s_cmp_eq_u32 s40, 12
	s_cselect_b32 s40, s87, vcc_lo
	s_cselect_b32 s91, s83, s9
	s_cselect_b32 s90, s82, s8
	s_cselect_b32 s41, s81, vcc_hi
	v_lshl_add_u64 v[212:213], s[88:89], 0, v[190:191]
	v_lshl_add_u64 v[212:213], v[212:213], 0, s[46:47]
	s_add_i32 m0, s19, 0xc000
	ds_read_b128 v[162:165], v211
	ds_read_b128 v[166:169], v211 offset:1024
	ds_read_b128 v[170:173], v211 offset:2048
	ds_read_b128 v[174:177], v211 offset:3072
	ds_read_b128 v[178:181], v211 offset:4096
	ds_read_b128 v[182:185], v211 offset:5120
	ds_read_b128 v[202:205], v211 offset:6144
	ds_read_b128 v[206:209], v211 offset:7168
	global_load_lds_dwordx4 v[212:213], off
	v_lshl_add_u64 v[212:213], s[88:89], 0, v[192:193]
	v_lshl_add_u64 v[212:213], v[212:213], 0, s[46:47]
	s_add_i32 m0, s19, 0xe000
	s_nop 0
	global_load_lds_dwordx4 v[212:213], off
	s_waitcnt vmcnt(8)
	s_waitcnt lgkmcnt(0)
	s_barrier
	s_setprio 1
	s_waitcnt lgkmcnt(0)
	v_mfma_f32_16x16x32_bf16 v[126:129], v[130:133], v[162:165], v[126:129]
	v_mfma_f32_16x16x32_bf16 v[122:125], v[138:141], v[162:165], v[122:125]
	v_mfma_f32_16x16x32_bf16 v[108:111], v[130:133], v[170:173], v[108:111]
	v_mfma_f32_16x16x32_bf16 v[104:107], v[138:141], v[170:173], v[104:107]
	v_mfma_f32_16x16x32_bf16 v[92:95], v[130:133], v[178:181], v[92:95]
	v_mfma_f32_16x16x32_bf16 v[88:91], v[138:141], v[178:181], v[88:91]
	v_mfma_f32_16x16x32_bf16 v[76:79], v[130:133], v[202:205], v[76:79]
	v_mfma_f32_16x16x32_bf16 v[72:75], v[138:141], v[202:205], v[72:75]
	v_mfma_f32_16x16x32_bf16 v[126:129], v[134:137], v[166:169], v[126:129]
	v_mfma_f32_16x16x32_bf16 v[122:125], v[142:145], v[166:169], v[122:125]
	v_mfma_f32_16x16x32_bf16 v[108:111], v[134:137], v[174:177], v[108:111]
	v_mfma_f32_16x16x32_bf16 v[104:107], v[142:145], v[174:177], v[104:107]
	v_mfma_f32_16x16x32_bf16 v[92:95], v[134:137], v[182:185], v[92:95]
	v_mfma_f32_16x16x32_bf16 v[88:91], v[142:145], v[182:185], v[88:91]
	v_mfma_f32_16x16x32_bf16 v[76:79], v[134:137], v[206:209], v[76:79]
	v_mfma_f32_16x16x32_bf16 v[72:75], v[142:145], v[206:209], v[72:75]
	v_mfma_f32_16x16x32_bf16 v[118:121], v[146:149], v[162:165], v[118:121]
	v_mfma_f32_16x16x32_bf16 v[114:117], v[154:157], v[162:165], v[114:117]
	v_mfma_f32_16x16x32_bf16 v[100:103], v[146:149], v[170:173], v[100:103]
	v_mfma_f32_16x16x32_bf16 v[96:99], v[154:157], v[170:173], v[96:99]
	v_mfma_f32_16x16x32_bf16 v[84:87], v[146:149], v[178:181], v[84:87]
	v_mfma_f32_16x16x32_bf16 v[80:83], v[154:157], v[178:181], v[80:83]
	v_mfma_f32_16x16x32_bf16 v[68:71], v[146:149], v[202:205], v[68:71]
	v_mfma_f32_16x16x32_bf16 v[64:67], v[154:157], v[202:205], v[64:67]
	v_mfma_f32_16x16x32_bf16 v[118:121], v[150:153], v[166:169], v[118:121]
	v_mfma_f32_16x16x32_bf16 v[114:117], v[158:161], v[166:169], v[114:117]
	v_mfma_f32_16x16x32_bf16 v[100:103], v[150:153], v[174:177], v[100:103]
	v_mfma_f32_16x16x32_bf16 v[96:99], v[158:161], v[174:177], v[96:99]
	v_mfma_f32_16x16x32_bf16 v[84:87], v[150:153], v[182:185], v[84:87]
	v_mfma_f32_16x16x32_bf16 v[80:83], v[158:161], v[182:185], v[80:83]
	v_mfma_f32_16x16x32_bf16 v[68:71], v[150:153], v[206:209], v[68:71]
	v_mfma_f32_16x16x32_bf16 v[64:67], v[158:161], v[206:209], v[64:67]
	s_setprio 0
	s_barrier
	s_add_i32 s8, s13, s11
	v_lshl_add_u64 v[212:213], s[40:41], 0, v[112:113]
	s_mov_b32 m0, s8
	ds_read_b128 v[162:165], v211 offset:16384
	ds_read_b128 v[166:169], v211 offset:17408
	ds_read_b128 v[170:173], v211 offset:18432
	ds_read_b128 v[174:177], v211 offset:19456
	ds_read_b128 v[178:181], v211 offset:20480
	ds_read_b128 v[182:185], v211 offset:21504
	ds_read_b128 v[202:205], v211 offset:22528
	ds_read_b128 v[206:209], v211 offset:23552
	global_load_lds_dwordx4 v112, s[40:41]
	s_add_i32 m0, s8, 0x2000
	s_add_u32 s8, s40, 0x40000
	v_lshl_add_u64 v[214:215], s[40:41], 0, v[200:201]
	s_addc_u32 s9, s41, 0
	s_add_i32 s13, s15, s11
	global_load_lds_dwordx4 v200, s[40:41]
	s_mov_b32 m0, s13
	v_lshl_add_u64 v[236:237], s[90:91], 0, v[188:189]
	global_load_lds_dwordx4 v112, s[8:9]
	s_add_i32 m0, s13, 0x2000
	s_nop 0
	global_load_lds_dwordx4 v200, s[8:9]
	s_mov_b32 m0, s19
	s_nop 0
	global_load_lds_dwordx4 v186, s[90:91]
	s_mov_b32 m0, s23
	s_nop 0
	global_load_lds_dwordx4 v188, s[90:91]
	s_waitcnt vmcnt(8)
	s_waitcnt lgkmcnt(0)
	s_barrier
; #define PG8_STAGE(bufoff, gbase, voff) do { _Pragma("unroll") for (int _i = 0; _i < 2; ++_i) \
;         __builtin_amdgcn_global_load_lds((const unsigned*)((const char*)(gbase) + (voff)[_i]), (LAS unsigned*)(lds + (bufoff) + ldsw + _i * 8192), 16, 0, 0); } while (0)
; #define PG8_LDA(dst, b, h) do { _Pragma("unroll") for (int m = 0; m < 4; ++m) _Pragma("unroll") for (int k = 0; k < 2; ++k) dst[m][k] = *(const LAS bf16x8*)(lds + PG8_SA(b, h) + aoff + m * 2048 + k * 1024); } while (0)
; #define PG8_LDB(dst, b, h) do { _Pragma("unroll") for (int n = 0; n < 2; ++n) _Pragma("unroll") for (int k = 0; k < 2; ++k) dst[n][k] = *(const LAS bf16x8*)(lds + PG8_SB(b, h) + boff + n * 2048 + k * 1024); } while (0)
; #define PG8_MMA(ai, bj, At, Bt) do { __builtin_amdgcn_s_setprio(1); _Pragma("unroll") for (int m = 0; m < 4; ++m) _Pragma("unroll") for (int n = 0; n < 2; ++n) _Pragma("unroll") for (int k = 0; k < 2; ++k) \
;         acc[ai][bj][m][n] = __builtin_amdgcn_mfma_f32_16x16x32_bf16(Bt[n][k], At[m][k], acc[ai][bj][m][n], 0, 0, 0); __builtin_amdgcn_s_setprio(0); } while (0)
; #define PG8_WAIT_V(n) asm volatile("s_waitcnt vmcnt(" #n ")" ::: "memory")
; #define PG8_WAIT_L(n) asm volatile("s_waitcnt lgkmcnt(" #n ")" ::: "memory")
; #define PG8_BAR __builtin_amdgcn_s_barrier()
; #define PG8_SCHED __builtin_amdgcn_sched_barrier(0)
; template <class Epi>
; __device__ __forceinline__ void gemm_phase(LAS unsigned char* lds, const Gemm g, const StaticOrder& S, const Epi& E, const int tid) {
;     ...
;             PG8_WAIT_V(8); PG8_WAIT_L(0); PG8_BAR; PG8_MMA(1, 0, At, B0); PG8_MMA(1, 1, At, B1); PG8_BAR; PG8_SCHED;
;             PG8_LDB(B0, 1, 0); PG8_LDB(B1, 1, 1); PG8_SCHED; PG8_LDA(At, 1, 0); PG8_STAGE(PG8_SA(0, 1), a2 + hstepA, voffA);
;             PG8_WAIT_V(8); PG8_WAIT_L(0); PG8_BAR; PG8_MMA(0, 0, At, B0); PG8_MMA(0, 1, At, B1); PG8_BAR; PG8_SCHED;
	s_setprio 1
	s_waitcnt lgkmcnt(0)
	v_mfma_f32_16x16x32_bf16 v[60:63], v[130:133], v[162:165], v[60:63]
	v_mfma_f32_16x16x32_bf16 v[56:59], v[138:141], v[162:165], v[56:59]
	v_mfma_f32_16x16x32_bf16 v[44:47], v[130:133], v[170:173], v[44:47]
	v_mfma_f32_16x16x32_bf16 v[40:43], v[138:141], v[170:173], v[40:43]
	v_mfma_f32_16x16x32_bf16 v[28:31], v[130:133], v[178:181], v[28:31]
	v_mfma_f32_16x16x32_bf16 v[24:27], v[138:141], v[178:181], v[24:27]
	v_mfma_f32_16x16x32_bf16 v[12:15], v[130:133], v[202:205], v[12:15]
	v_mfma_f32_16x16x32_bf16 v[8:11], v[138:141], v[202:205], v[8:11]
	v_mfma_f32_16x16x32_bf16 v[60:63], v[134:137], v[166:169], v[60:63]
	v_mfma_f32_16x16x32_bf16 v[56:59], v[142:145], v[166:169], v[56:59]
	v_mfma_f32_16x16x32_bf16 v[44:47], v[134:137], v[174:177], v[44:47]
	v_mfma_f32_16x16x32_bf16 v[40:43], v[142:145], v[174:177], v[40:43]
	v_mfma_f32_16x16x32_bf16 v[28:31], v[134:137], v[182:185], v[28:31]
	v_mfma_f32_16x16x32_bf16 v[24:27], v[142:145], v[182:185], v[24:27]
	v_mfma_f32_16x16x32_bf16 v[12:15], v[134:137], v[206:209], v[12:15]
	v_mfma_f32_16x16x32_bf16 v[8:11], v[142:145], v[206:209], v[8:11]
	v_mfma_f32_16x16x32_bf16 v[52:55], v[146:149], v[162:165], v[52:55]
	v_mfma_f32_16x16x32_bf16 v[48:51], v[154:157], v[162:165], v[48:51]
	v_mfma_f32_16x16x32_bf16 v[36:39], v[146:149], v[170:173], v[36:39]
	v_mfma_f32_16x16x32_bf16 v[32:35], v[154:157], v[170:173], v[32:35]
	v_mfma_f32_16x16x32_bf16 v[20:23], v[146:149], v[178:181], v[20:23]
	v_mfma_f32_16x16x32_bf16 v[16:19], v[154:157], v[178:181], v[16:19]
	v_mfma_f32_16x16x32_bf16 v[4:7], v[146:149], v[202:205], v[4:7]
	v_mfma_f32_16x16x32_bf16 v[0:3], v[154:157], v[202:205], v[0:3]
	v_mfma_f32_16x16x32_bf16 v[52:55], v[150:153], v[166:169], v[52:55]
	v_mfma_f32_16x16x32_bf16 v[48:51], v[158:161], v[166:169], v[48:51]
	v_mfma_f32_16x16x32_bf16 v[36:39], v[150:153], v[174:177], v[36:39]
	v_mfma_f32_16x16x32_bf16 v[32:35], v[158:161], v[174:177], v[32:35]
	v_mfma_f32_16x16x32_bf16 v[20:23], v[150:153], v[182:185], v[20:23]
	v_mfma_f32_16x16x32_bf16 v[16:19], v[158:161], v[182:185], v[16:19]
	v_mfma_f32_16x16x32_bf16 v[4:7], v[150:153], v[206:209], v[4:7]
	v_mfma_f32_16x16x32_bf16 v[0:3], v[158:161], v[206:209], v[0:3]
	s_setprio 0
	s_barrier
	s_add_i32 s13, 0, 0x18000
	s_add_i32 s31, 0, 0x1c000
	v_add_u32_e32 v142, s13, v210
	v_add_u32_e32 v158, s31, v210
	ds_read_b128 v[130:133], v142
	ds_read_b128 v[134:137], v142 offset:1024
	ds_read_b128 v[138:141], v142 offset:2048
	ds_read_b128 v[142:145], v142 offset:3072
	ds_read_b128 v[146:149], v158
	ds_read_b128 v[150:153], v158 offset:1024
	ds_read_b128 v[154:157], v158 offset:2048
	ds_read_b128 v[158:161], v158 offset:3072
	s_add_u32 s8, s90, 0x90000
	s_addc_u32 s9, s91, 0
	s_mov_b32 m0, s28
	ds_read_b128 v[162:165], v211 offset:32768
	ds_read_b128 v[166:169], v211 offset:33792
	ds_read_b128 v[170:173], v211 offset:34816
	ds_read_b128 v[174:177], v211 offset:35840
	ds_read_b128 v[178:181], v211 offset:36864
	ds_read_b128 v[182:185], v211 offset:37888
	ds_read_b128 v[202:205], v211 offset:38912
	ds_read_b128 v[206:209], v211 offset:39936
	global_load_lds_dwordx4 v186, s[8:9]
	v_lshl_add_u64 v[238:239], s[8:9], 0, v[188:189]
	s_mov_b32 m0, s30
	s_nop 0
	global_load_lds_dwordx4 v188, s[8:9]
	s_waitcnt vmcnt(8)
	s_waitcnt lgkmcnt(0)
	s_barrier
	s_setprio 1
	s_waitcnt lgkmcnt(0)
	v_mfma_f32_16x16x32_bf16 v[126:129], v[130:133], v[162:165], v[126:129]
	v_mfma_f32_16x16x32_bf16 v[122:125], v[138:141], v[162:165], v[122:125]
	v_mfma_f32_16x16x32_bf16 v[108:111], v[130:133], v[170:173], v[108:111]
	v_mfma_f32_16x16x32_bf16 v[104:107], v[138:141], v[170:173], v[104:107]
	v_mfma_f32_16x16x32_bf16 v[92:95], v[130:133], v[178:181], v[92:95]
	v_mfma_f32_16x16x32_bf16 v[88:91], v[138:141], v[178:181], v[88:91]
	v_mfma_f32_16x16x32_bf16 v[76:79], v[130:133], v[202:205], v[76:79]
	v_mfma_f32_16x16x32_bf16 v[72:75], v[138:141], v[202:205], v[72:75]
	v_mfma_f32_16x16x32_bf16 v[126:129], v[134:137], v[166:169], v[126:129]
	v_mfma_f32_16x16x32_bf16 v[122:125], v[142:145], v[166:169], v[122:125]
	v_mfma_f32_16x16x32_bf16 v[108:111], v[134:137], v[174:177], v[108:111]
	v_mfma_f32_16x16x32_bf16 v[104:107], v[142:145], v[174:177], v[104:107]
	v_mfma_f32_16x16x32_bf16 v[92:95], v[134:137], v[182:185], v[92:95]
	v_mfma_f32_16x16x32_bf16 v[88:91], v[142:145], v[182:185], v[88:91]
	v_mfma_f32_16x16x32_bf16 v[76:79], v[134:137], v[206:209], v[76:79]
	v_mfma_f32_16x16x32_bf16 v[72:75], v[142:145], v[206:209], v[72:75]
	v_mfma_f32_16x16x32_bf16 v[118:121], v[146:149], v[162:165], v[118:121]
	v_mfma_f32_16x16x32_bf16 v[114:117], v[154:157], v[162:165], v[114:117]
	v_mfma_f32_16x16x32_bf16 v[100:103], v[146:149], v[170:173], v[100:103]
	v_mfma_f32_16x16x32_bf16 v[96:99], v[154:157], v[170:173], v[96:99]
	v_mfma_f32_16x16x32_bf16 v[84:87], v[146:149], v[178:181], v[84:87]
	v_mfma_f32_16x16x32_bf16 v[80:83], v[154:157], v[178:181], v[80:83]
	v_mfma_f32_16x16x32_bf16 v[68:71], v[146:149], v[202:205], v[68:71]
	v_mfma_f32_16x16x32_bf16 v[64:67], v[154:157], v[202:205], v[64:67]
	v_mfma_f32_16x16x32_bf16 v[118:121], v[150:153], v[166:169], v[118:121]
	v_mfma_f32_16x16x32_bf16 v[114:117], v[158:161], v[166:169], v[114:117]
	v_mfma_f32_16x16x32_bf16 v[100:103], v[150:153], v[174:177], v[100:103]
	v_mfma_f32_16x16x32_bf16 v[96:99], v[158:161], v[174:177], v[96:99]
	v_mfma_f32_16x16x32_bf16 v[84:87], v[150:153], v[182:185], v[84:87]
	v_mfma_f32_16x16x32_bf16 v[80:83], v[158:161], v[182:185], v[80:83]
	v_mfma_f32_16x16x32_bf16 v[68:71], v[150:153], v[206:209], v[68:71]
	v_mfma_f32_16x16x32_bf16 v[64:67], v[158:161], v[206:209], v[64:67]
	s_setprio 0
	s_barrier
; #define PG8_STAGE(bufoff, gbase, voff) do { _Pragma("unroll") for (int _i = 0; _i < 2; ++_i) \
;         __builtin_amdgcn_global_load_lds((const unsigned*)((const char*)(gbase) + (voff)[_i]), (LAS unsigned*)(lds + (bufoff) + ldsw + _i * 8192), 16, 0, 0); } while (0)
; #define PG8_LDA(dst, b, h) do { _Pragma("unroll") for (int m = 0; m < 4; ++m) _Pragma("unroll") for (int k = 0; k < 2; ++k) dst[m][k] = *(const LAS bf16x8*)(lds + PG8_SA(b, h) + aoff + m * 2048 + k * 1024); } while (0)
; #define PG8_MMA(ai, bj, At, Bt) do { __builtin_amdgcn_s_setprio(1); _Pragma("unroll") for (int m = 0; m < 4; ++m) _Pragma("unroll") for (int n = 0; n < 2; ++n) _Pragma("unroll") for (int k = 0; k < 2; ++k) \
;         acc[ai][bj][m][n] = __builtin_amdgcn_mfma_f32_16x16x32_bf16(Bt[n][k], At[m][k], acc[ai][bj][m][n], 0, 0, 0); __builtin_amdgcn_s_setprio(0); } while (0)
; #define PG8_WAIT_V(n) asm volatile("s_waitcnt vmcnt(" #n ")" ::: "memory")
; #define PG8_WAIT_L(n) asm volatile("s_waitcnt lgkmcnt(" #n ")" ::: "memory")
; #define PG8_BAR __builtin_amdgcn_s_barrier()
; #define PG8_SCHED __builtin_amdgcn_sched_barrier(0)
; template <class Epi>
; __device__ __forceinline__ void gemm_phase(LAS unsigned char* lds, const Gemm g, const StaticOrder& S, const Epi& E, const int tid) {
;     ...
;             PG8_LDA(At, 1, 1); PG8_STAGE(PG8_SB(1, 0), b3, voffB); PG8_STAGE(PG8_SB(1, 1), b3 + hstepB, voffB); PG8_STAGE(PG8_SA(1, 0), a3, voffA);
;             PG8_WAIT_V(8); PG8_WAIT_L(0); PG8_BAR; PG8_MMA(1, 0, At, B0); PG8_MMA(1, 1, At, B1); PG8_BAR; PG8_SCHED;
;         }
;         if (wr == 0) PG8_BAR;
	s_add_i32 s8, s13, s11
	s_add_u32 s100, s40, 0x80
	s_addc_u32 s101, s41, 0
	s_mov_b32 m0, s8
	ds_read_b128 v[162:165], v211 offset:49152
	ds_read_b128 v[166:169], v211 offset:50176
	ds_read_b128 v[170:173], v211 offset:51200
	ds_read_b128 v[174:177], v211 offset:52224
	ds_read_b128 v[178:181], v211 offset:53248
	ds_read_b128 v[182:185], v211 offset:54272
	ds_read_b128 v[202:205], v211 offset:55296
	ds_read_b128 v[206:209], v211 offset:56320
	global_load_lds_dwordx4 v112, s[100:101]
	s_add_i32 m0, s8, 0x2000
	s_add_u32 s8, s40, 0x40080
	v_lshl_add_u64 v[212:213], v[214:215], 0, s[24:25]
	s_addc_u32 s9, s41, 0
	s_add_i32 s13, s31, s11
	global_load_lds_dwordx4 v[212:213], off
	s_mov_b32 m0, s13
	s_nop 0
	global_load_lds_dwordx4 v112, s[8:9]
	s_add_i32 m0, s13, 0x2000
	s_nop 0
	global_load_lds_dwordx4 v200, s[8:9]
	s_add_u32 s100, s90, 0x80
	s_addc_u32 s101, s91, 0
	s_mov_b32 m0, s99
	s_nop 0
	global_load_lds_dwordx4 v186, s[100:101]
	s_add_u32 s100, s90, 0x80
	s_addc_u32 s101, s91, 0
	s_mov_b32 m0, s33
	s_nop 0
	global_load_lds_dwordx4 v188, s[100:101]
	s_waitcnt vmcnt(8)
	s_waitcnt lgkmcnt(0)
	s_barrier
	s_setprio 1
	s_waitcnt lgkmcnt(0)
	v_mfma_f32_16x16x32_bf16 v[60:63], v[130:133], v[162:165], v[60:63]
	v_mfma_f32_16x16x32_bf16 v[56:59], v[138:141], v[162:165], v[56:59]
	v_mfma_f32_16x16x32_bf16 v[44:47], v[130:133], v[170:173], v[44:47]
	v_mfma_f32_16x16x32_bf16 v[40:43], v[138:141], v[170:173], v[40:43]
	v_mfma_f32_16x16x32_bf16 v[28:31], v[130:133], v[178:181], v[28:31]
	v_mfma_f32_16x16x32_bf16 v[24:27], v[138:141], v[178:181], v[24:27]
	v_mfma_f32_16x16x32_bf16 v[12:15], v[130:133], v[202:205], v[12:15]
	v_mfma_f32_16x16x32_bf16 v[8:11], v[138:141], v[202:205], v[8:11]
	v_mfma_f32_16x16x32_bf16 v[60:63], v[134:137], v[166:169], v[60:63]
	v_mfma_f32_16x16x32_bf16 v[56:59], v[142:145], v[166:169], v[56:59]
	v_mfma_f32_16x16x32_bf16 v[44:47], v[134:137], v[174:177], v[44:47]
	v_mfma_f32_16x16x32_bf16 v[40:43], v[142:145], v[174:177], v[40:43]
	v_mfma_f32_16x16x32_bf16 v[28:31], v[134:137], v[182:185], v[28:31]
	v_mfma_f32_16x16x32_bf16 v[24:27], v[142:145], v[182:185], v[24:27]
	v_mfma_f32_16x16x32_bf16 v[12:15], v[134:137], v[206:209], v[12:15]
	v_mfma_f32_16x16x32_bf16 v[8:11], v[142:145], v[206:209], v[8:11]
	v_mfma_f32_16x16x32_bf16 v[52:55], v[146:149], v[162:165], v[52:55]
	v_mfma_f32_16x16x32_bf16 v[48:51], v[154:157], v[162:165], v[48:51]
	v_mfma_f32_16x16x32_bf16 v[36:39], v[146:149], v[170:173], v[36:39]
	v_mfma_f32_16x16x32_bf16 v[32:35], v[154:157], v[170:173], v[32:35]
	v_mfma_f32_16x16x32_bf16 v[20:23], v[146:149], v[178:181], v[20:23]
	v_mfma_f32_16x16x32_bf16 v[16:19], v[154:157], v[178:181], v[16:19]
	v_mfma_f32_16x16x32_bf16 v[4:7], v[146:149], v[202:205], v[4:7]
	v_mfma_f32_16x16x32_bf16 v[0:3], v[154:157], v[202:205], v[0:3]
	v_mfma_f32_16x16x32_bf16 v[52:55], v[150:153], v[166:169], v[52:55]
	v_mfma_f32_16x16x32_bf16 v[48:51], v[158:161], v[166:169], v[48:51]
	v_mfma_f32_16x16x32_bf16 v[36:39], v[150:153], v[174:177], v[36:39]
	v_mfma_f32_16x16x32_bf16 v[32:35], v[158:161], v[174:177], v[32:35]
	v_mfma_f32_16x16x32_bf16 v[20:23], v[150:153], v[182:185], v[20:23]
	v_mfma_f32_16x16x32_bf16 v[16:19], v[158:161], v[182:185], v[16:19]
	v_mfma_f32_16x16x32_bf16 v[4:7], v[150:153], v[206:209], v[4:7]
	v_mfma_f32_16x16x32_bf16 v[0:3], v[158:161], v[206:209], v[0:3]
	s_setprio 0
	s_barrier
	s_add_u32 s88, s88, 0x100
	s_addc_u32 s89, s89, 0
	s_add_u32 vcc_lo, vcc_lo, 0x100
	s_addc_u32 vcc_hi, vcc_hi, 0
	s_cmp_gt_u32 s96, 13
	s_mov_b32 s40, s96
	s_cbranch_scc0 .LBB0_230
	s_and_b64 vcc, exec, s[44:45]
	s_cbranch_vccz .LBB0_233
	s_barrier

; #define PG8_STAGE(bufoff, gbase, voff) do { _Pragma("unroll") for (int _i = 0; _i < 2; ++_i) \
;         __builtin_amdgcn_global_load_lds((const unsigned*)((const char*)(gbase) + (voff)[_i]), (LAS unsigned*)(lds + (bufoff) + ldsw + _i * 8192), 16, 0, 0); } while (0)
; #define PG8_LDA(dst, b, h) do { _Pragma("unroll") for (int m = 0; m < 4; ++m) _Pragma("unroll") for (int k = 0; k < 2; ++k) dst[m][k] = *(const LAS bf16x8*)(lds + PG8_SA(b, h) + aoff + m * 2048 + k * 1024); } while (0)
; #define PG8_LDB(dst, b, h) do { _Pragma("unroll") for (int n = 0; n < 2; ++n) _Pragma("unroll") for (int k = 0; k < 2; ++k) dst[n][k] = *(const LAS bf16x8*)(lds + PG8_SB(b, h) + boff + n * 2048 + k * 1024); } while (0)
; #define PG8_MMA(ai, bj, At, Bt) do { __builtin_amdgcn_s_setprio(1); _Pragma("unroll") for (int m = 0; m < 4; ++m) _Pragma("unroll") for (int n = 0; n < 2; ++n) _Pragma("unroll") for (int k = 0; k < 2; ++k) \
;         acc[ai][bj][m][n] = __builtin_amdgcn_mfma_f32_16x16x32_bf16(Bt[n][k], At[m][k], acc[ai][bj][m][n], 0, 0, 0); __builtin_amdgcn_s_setprio(0); } while (0)
; #define PG8_WAIT_V(n) asm volatile("s_waitcnt vmcnt(" #n ")" ::: "memory")
; #define PG8_WAIT_L(n) asm volatile("s_waitcnt lgkmcnt(" #n ")" ::: "memory")
; #define PG8_BAR __builtin_amdgcn_s_barrier()
; #define PG8_SCHED __builtin_amdgcn_sched_barrier(0)
; template <class Epi>
; __device__ __forceinline__ void gemm_phase(LAS unsigned char* lds, const Gemm g, const StaticOrder& S, const Epi& E, const int tid) {
;     ...
;             const char* a1 = cA + (size_t)(t + 1) * kstep + ((t + 1) >= 8 ? xtra : 0);
;             const char* a2 = last ? nA : cA + (size_t)(t + 2) * kstep + ((t + 2) >= 8 ? xtra : 0); const char* b2 = last ? nB : cB + (size_t)(t + 2) * kstep;
;             const char* a3 = a2 + kstep; const char* b3 = b2 + kstep;
;             PG8_LDB(B0, 0, 0); PG8_LDB(B1, 0, 1); PG8_SCHED; PG8_LDA(At, 0, 0); PG8_STAGE(PG8_SA(1, 1), a1 + hstepA, voffA);
;             PG8_WAIT_V(8); PG8_WAIT_L(0); PG8_BAR; PG8_MMA(0, 0, At, B0); PG8_MMA(0, 1, At, B1); PG8_BAR; PG8_SCHED;
;             PG8_LDA(At, 0, 1); PG8_STAGE(PG8_SB(0, 0), b2, voffB); PG8_STAGE(PG8_SB(0, 1), b2 + hstepB, voffB); PG8_STAGE(PG8_SA(0, 0), a2, voffA);
;             PG8_WAIT_V(8); PG8_WAIT_L(0); PG8_BAR; PG8_MMA(1, 0, At, B0); PG8_MMA(1, 1, At, B1); PG8_BAR; PG8_SCHED;
.LBB0_268:
	s_add_u32 s8, s40, 0xfffc0080
	s_addc_u32 s9, s41, -1
	s_add_i32 s13, 0, 0x10000
	v_add_u32_e32 v162, s13, v167
	ds_read_b128 v[150:153], v162
	ds_read_b128 v[154:157], v162 offset:1024
	ds_read_b128 v[158:161], v162 offset:2048
	ds_read_b128 v[170:173], v162 offset:3072
	v_add_u32_e32 v162, s15, v167
	ds_read_b128 v[174:177], v162
	ds_read_b128 v[178:181], v162 offset:1024
	ds_read_b128 v[182:185], v162 offset:2048
	ds_read_b128 v[186:189], v162 offset:3072
	s_cmp_eq_u32 s85, 12
	s_cselect_b32 vcc_hi, s33, s9
	s_cselect_b32 vcc_lo, s36, s8
	s_cselect_b32 s95, s37, s57
	s_cselect_b32 s94, s45, s46
	s_add_i32 m0, s11, 0xc000
	ds_read_b128 v[190:193], v169
	ds_read_b128 v[200:203], v169 offset:1024
	ds_read_b128 v[204:207], v169 offset:2048
	ds_read_b128 v[208:211], v169 offset:3072
	ds_read_b128 v[212:215], v169 offset:4096
	ds_read_b128 v[234:237], v169 offset:5120
	ds_read_b128 v[238:241], v169 offset:6144
	ds_read_b128 v[242:245], v169 offset:7168
	global_load_lds_dwordx4 v146, s[40:41]
	s_add_i32 m0, s11, 0xe000
	s_nop 0
	global_load_lds_dwordx4 v148, s[40:41]
	s_waitcnt vmcnt(8)
	s_waitcnt lgkmcnt(0)
	s_barrier
	s_setprio 1
	s_waitcnt lgkmcnt(0)
	v_mfma_f32_16x16x32_bf16 v[134:137], v[150:153], v[190:193], v[134:137]
	v_mfma_f32_16x16x32_bf16 v[130:133], v[158:161], v[190:193], v[130:133]
	v_mfma_f32_16x16x32_bf16 v[118:121], v[150:153], v[204:207], v[118:121]
	v_mfma_f32_16x16x32_bf16 v[114:117], v[158:161], v[204:207], v[114:117]
	v_mfma_f32_16x16x32_bf16 v[100:103], v[150:153], v[212:215], v[100:103]
	v_mfma_f32_16x16x32_bf16 v[96:99], v[158:161], v[212:215], v[96:99]
	v_mfma_f32_16x16x32_bf16 v[84:87], v[150:153], v[238:241], v[84:87]
	v_mfma_f32_16x16x32_bf16 v[80:83], v[158:161], v[238:241], v[80:83]
	v_mfma_f32_16x16x32_bf16 v[134:137], v[154:157], v[200:203], v[134:137]
	v_mfma_f32_16x16x32_bf16 v[130:133], v[170:173], v[200:203], v[130:133]
	v_mfma_f32_16x16x32_bf16 v[118:121], v[154:157], v[208:211], v[118:121]
	v_mfma_f32_16x16x32_bf16 v[114:117], v[170:173], v[208:211], v[114:117]
	v_mfma_f32_16x16x32_bf16 v[100:103], v[154:157], v[234:237], v[100:103]
	v_mfma_f32_16x16x32_bf16 v[96:99], v[170:173], v[234:237], v[96:99]
	v_mfma_f32_16x16x32_bf16 v[84:87], v[154:157], v[242:245], v[84:87]
	v_mfma_f32_16x16x32_bf16 v[80:83], v[170:173], v[242:245], v[80:83]
	v_mfma_f32_16x16x32_bf16 v[126:129], v[174:177], v[190:193], v[126:129]
	v_mfma_f32_16x16x32_bf16 v[122:125], v[182:185], v[190:193], v[122:125]
	v_mfma_f32_16x16x32_bf16 v[108:111], v[174:177], v[204:207], v[108:111]
	v_mfma_f32_16x16x32_bf16 v[104:107], v[182:185], v[204:207], v[104:107]
	v_mfma_f32_16x16x32_bf16 v[92:95], v[174:177], v[212:215], v[92:95]
	v_mfma_f32_16x16x32_bf16 v[88:91], v[182:185], v[212:215], v[88:91]
	v_mfma_f32_16x16x32_bf16 v[76:79], v[174:177], v[238:241], v[76:79]
	v_mfma_f32_16x16x32_bf16 v[72:75], v[182:185], v[238:241], v[72:75]
	v_mfma_f32_16x16x32_bf16 v[126:129], v[178:181], v[200:203], v[126:129]
	v_mfma_f32_16x16x32_bf16 v[122:125], v[186:189], v[200:203], v[122:125]
	v_mfma_f32_16x16x32_bf16 v[108:111], v[178:181], v[208:211], v[108:111]
	v_mfma_f32_16x16x32_bf16 v[104:107], v[186:189], v[208:211], v[104:107]
	v_mfma_f32_16x16x32_bf16 v[92:95], v[178:181], v[234:237], v[92:95]
	v_mfma_f32_16x16x32_bf16 v[88:91], v[186:189], v[234:237], v[88:91]
	v_mfma_f32_16x16x32_bf16 v[76:79], v[178:181], v[242:245], v[76:79]
	v_mfma_f32_16x16x32_bf16 v[72:75], v[186:189], v[242:245], v[72:75]
	s_setprio 0
	s_barrier
	s_add_i32 s8, s13, s81
	s_mov_b32 m0, s8
	ds_read_b128 v[190:193], v169 offset:16384
	ds_read_b128 v[200:203], v169 offset:17408
	ds_read_b128 v[204:207], v169 offset:18432
	ds_read_b128 v[208:211], v169 offset:19456
	ds_read_b128 v[212:215], v169 offset:20480
	ds_read_b128 v[234:237], v169 offset:21504
	ds_read_b128 v[238:241], v169 offset:22528
	ds_read_b128 v[242:245], v169 offset:23552
	global_load_lds_dwordx4 v112, s[94:95]
	s_add_i32 m0, s8, 0x2000
	s_add_u32 s8, s94, 0x40000
	v_lshl_add_u64 v[228:229], s[94:95], 0, v[142:143]
	s_addc_u32 s9, s95, 0
	s_add_i32 s13, s15, s81
	global_load_lds_dwordx4 v142, s[94:95]
	s_mov_b32 m0, s13
	s_nop 0
	global_load_lds_dwordx4 v112, s[8:9]
	s_add_i32 m0, s13, 0x2000
	s_nop 0
	global_load_lds_dwordx4 v142, s[8:9]
	s_mov_b32 m0, s11
	s_nop 0
	global_load_lds_dwordx4 v138, vcc
	s_mov_b32 m0, s19
	s_nop 0
	global_load_lds_dwordx4 v140, vcc
	s_waitcnt vmcnt(8)
	s_waitcnt lgkmcnt(0)
	s_barrier
	s_setprio 1
	s_waitcnt lgkmcnt(0)
	v_mfma_f32_16x16x32_bf16 v[68:71], v[150:153], v[190:193], v[68:71]
	v_mfma_f32_16x16x32_bf16 v[64:67], v[158:161], v[190:193], v[64:67]
	v_mfma_f32_16x16x32_bf16 v[52:55], v[150:153], v[204:207], v[52:55]
	v_mfma_f32_16x16x32_bf16 v[48:51], v[158:161], v[204:207], v[48:51]
	v_mfma_f32_16x16x32_bf16 v[36:39], v[150:153], v[212:215], v[36:39]
	v_mfma_f32_16x16x32_bf16 v[32:35], v[158:161], v[212:215], v[32:35]
	v_mfma_f32_16x16x32_bf16 v[20:23], v[150:153], v[238:241], v[20:23]
	v_mfma_f32_16x16x32_bf16 v[16:19], v[158:161], v[238:241], v[16:19]
	v_mfma_f32_16x16x32_bf16 v[68:71], v[154:157], v[200:203], v[68:71]
	v_mfma_f32_16x16x32_bf16 v[64:67], v[170:173], v[200:203], v[64:67]
	v_mfma_f32_16x16x32_bf16 v[52:55], v[154:157], v[208:211], v[52:55]
	v_mfma_f32_16x16x32_bf16 v[48:51], v[170:173], v[208:211], v[48:51]
	v_mfma_f32_16x16x32_bf16 v[36:39], v[154:157], v[234:237], v[36:39]
	v_mfma_f32_16x16x32_bf16 v[32:35], v[170:173], v[234:237], v[32:35]
	v_mfma_f32_16x16x32_bf16 v[20:23], v[154:157], v[242:245], v[20:23]
	v_mfma_f32_16x16x32_bf16 v[16:19], v[170:173], v[242:245], v[16:19]
	v_mfma_f32_16x16x32_bf16 v[60:63], v[174:177], v[190:193], v[60:63]
	v_mfma_f32_16x16x32_bf16 v[56:59], v[182:185], v[190:193], v[56:59]
	v_mfma_f32_16x16x32_bf16 v[44:47], v[174:177], v[204:207], v[44:47]
	v_mfma_f32_16x16x32_bf16 v[40:43], v[182:185], v[204:207], v[40:43]
	v_mfma_f32_16x16x32_bf16 v[28:31], v[174:177], v[212:215], v[28:31]
	v_mfma_f32_16x16x32_bf16 v[24:27], v[182:185], v[212:215], v[24:27]
	v_mfma_f32_16x16x32_bf16 v[12:15], v[174:177], v[238:241], v[12:15]
	v_mfma_f32_16x16x32_bf16 v[8:11], v[182:185], v[238:241], v[8:11]
	v_mfma_f32_16x16x32_bf16 v[60:63], v[178:181], v[200:203], v[60:63]
	v_mfma_f32_16x16x32_bf16 v[56:59], v[186:189], v[200:203], v[56:59]
	v_mfma_f32_16x16x32_bf16 v[44:47], v[178:181], v[208:211], v[44:47]
	v_mfma_f32_16x16x32_bf16 v[40:43], v[186:189], v[208:211], v[40:43]
	v_mfma_f32_16x16x32_bf16 v[28:31], v[178:181], v[234:237], v[28:31]
	v_mfma_f32_16x16x32_bf16 v[24:27], v[186:189], v[234:237], v[24:27]
	v_mfma_f32_16x16x32_bf16 v[12:15], v[178:181], v[242:245], v[12:15]
	v_mfma_f32_16x16x32_bf16 v[8:11], v[186:189], v[242:245], v[8:11]
	s_setprio 0
	s_barrier
; #define PG8_STAGE(bufoff, gbase, voff) do { _Pragma("unroll") for (int _i = 0; _i < 2; ++_i) \
;         __builtin_amdgcn_global_load_lds((const unsigned*)((const char*)(gbase) + (voff)[_i]), (LAS unsigned*)(lds + (bufoff) + ldsw + _i * 8192), 16, 0, 0); } while (0)
; #define PG8_LDA(dst, b, h) do { _Pragma("unroll") for (int m = 0; m < 4; ++m) _Pragma("unroll") for (int k = 0; k < 2; ++k) dst[m][k] = *(const LAS bf16x8*)(lds + PG8_SA(b, h) + aoff + m * 2048 + k * 1024); } while (0)
; #define PG8_LDB(dst, b, h) do { _Pragma("unroll") for (int n = 0; n < 2; ++n) _Pragma("unroll") for (int k = 0; k < 2; ++k) dst[n][k] = *(const LAS bf16x8*)(lds + PG8_SB(b, h) + boff + n * 2048 + k * 1024); } while (0)
; #define PG8_MMA(ai, bj, At, Bt) do { __builtin_amdgcn_s_setprio(1); _Pragma("unroll") for (int m = 0; m < 4; ++m) _Pragma("unroll") for (int n = 0; n < 2; ++n) _Pragma("unroll") for (int k = 0; k < 2; ++k) \
;         acc[ai][bj][m][n] = __builtin_amdgcn_mfma_f32_16x16x32_bf16(Bt[n][k], At[m][k], acc[ai][bj][m][n], 0, 0, 0); __builtin_amdgcn_s_setprio(0); } while (0)
; #define PG8_WAIT_V(n) asm volatile("s_waitcnt vmcnt(" #n ")" ::: "memory")
; #define PG8_WAIT_L(n) asm volatile("s_waitcnt lgkmcnt(" #n ")" ::: "memory")
; #define PG8_BAR __builtin_amdgcn_s_barrier()
; #define PG8_SCHED __builtin_amdgcn_sched_barrier(0)
; template <class Epi>
; __device__ __forceinline__ void gemm_phase(LAS unsigned char* lds, const Gemm g, const StaticOrder& S, const Epi& E, const int tid) {
;     ...
;             PG8_LDB(B0, 1, 0); PG8_LDB(B1, 1, 1); PG8_SCHED; PG8_LDA(At, 1, 0); PG8_STAGE(PG8_SA(0, 1), a2 + hstepA, voffA);
;             PG8_WAIT_V(8); PG8_WAIT_L(0); PG8_BAR; PG8_MMA(0, 0, At, B0); PG8_MMA(0, 1, At, B1); PG8_BAR; PG8_SCHED;
;             PG8_LDA(At, 1, 1); PG8_STAGE(PG8_SB(1, 0), b3, voffB); PG8_STAGE(PG8_SB(1, 1), b3 + hstepB, voffB); PG8_STAGE(PG8_SA(1, 0), a3, voffA);
;             PG8_WAIT_V(8); PG8_WAIT_L(0); PG8_BAR; PG8_MMA(1, 0, At, B0); PG8_MMA(1, 1, At, B1); PG8_BAR; PG8_SCHED;
;         }
;         if (wr == 0) PG8_BAR;
	s_add_i32 s13, 0, 0x18000
	s_add_i32 s31, 0, 0x1c000
	v_add_u32_e32 v170, s13, v167
	v_add_u32_e32 v186, s31, v167
	ds_read_b128 v[150:153], v170
	ds_read_b128 v[154:157], v170 offset:1024
	ds_read_b128 v[158:161], v170 offset:2048
	ds_read_b128 v[170:173], v170 offset:3072
	ds_read_b128 v[174:177], v186
	ds_read_b128 v[178:181], v186 offset:1024
	ds_read_b128 v[182:185], v186 offset:2048
	ds_read_b128 v[186:189], v186 offset:3072
	s_add_u32 s8, vcc_lo, 0x40000
	s_addc_u32 s9, vcc_hi, 0
	s_mov_b32 m0, s98
	ds_read_b128 v[190:193], v169 offset:32768
	ds_read_b128 v[200:203], v169 offset:33792
	ds_read_b128 v[204:207], v169 offset:34816
	ds_read_b128 v[208:211], v169 offset:35840
	ds_read_b128 v[212:215], v169 offset:36864
	ds_read_b128 v[234:237], v169 offset:37888
	ds_read_b128 v[238:241], v169 offset:38912
	ds_read_b128 v[242:245], v169 offset:39936
	global_load_lds_dwordx4 v138, s[8:9]
	s_mov_b32 m0, s99
	s_nop 0
	global_load_lds_dwordx4 v140, s[8:9]
	s_waitcnt vmcnt(8)
	s_waitcnt lgkmcnt(0)
	s_barrier
	s_setprio 1
	s_waitcnt lgkmcnt(0)
	v_mfma_f32_16x16x32_bf16 v[134:137], v[150:153], v[190:193], v[134:137]
	v_mfma_f32_16x16x32_bf16 v[130:133], v[158:161], v[190:193], v[130:133]
	v_mfma_f32_16x16x32_bf16 v[118:121], v[150:153], v[204:207], v[118:121]
	v_mfma_f32_16x16x32_bf16 v[114:117], v[158:161], v[204:207], v[114:117]
	v_mfma_f32_16x16x32_bf16 v[100:103], v[150:153], v[212:215], v[100:103]
	v_mfma_f32_16x16x32_bf16 v[96:99], v[158:161], v[212:215], v[96:99]
	v_mfma_f32_16x16x32_bf16 v[84:87], v[150:153], v[238:241], v[84:87]
	v_mfma_f32_16x16x32_bf16 v[80:83], v[158:161], v[238:241], v[80:83]
	v_mfma_f32_16x16x32_bf16 v[134:137], v[154:157], v[200:203], v[134:137]
	v_mfma_f32_16x16x32_bf16 v[130:133], v[170:173], v[200:203], v[130:133]
	v_mfma_f32_16x16x32_bf16 v[118:121], v[154:157], v[208:211], v[118:121]
	v_mfma_f32_16x16x32_bf16 v[114:117], v[170:173], v[208:211], v[114:117]
	v_mfma_f32_16x16x32_bf16 v[100:103], v[154:157], v[234:237], v[100:103]
	v_mfma_f32_16x16x32_bf16 v[96:99], v[170:173], v[234:237], v[96:99]
	v_mfma_f32_16x16x32_bf16 v[84:87], v[154:157], v[242:245], v[84:87]
	v_mfma_f32_16x16x32_bf16 v[80:83], v[170:173], v[242:245], v[80:83]
	v_mfma_f32_16x16x32_bf16 v[126:129], v[174:177], v[190:193], v[126:129]
	v_mfma_f32_16x16x32_bf16 v[122:125], v[182:185], v[190:193], v[122:125]
	v_mfma_f32_16x16x32_bf16 v[108:111], v[174:177], v[204:207], v[108:111]
	v_mfma_f32_16x16x32_bf16 v[104:107], v[182:185], v[204:207], v[104:107]
	v_mfma_f32_16x16x32_bf16 v[92:95], v[174:177], v[212:215], v[92:95]
	v_mfma_f32_16x16x32_bf16 v[88:91], v[182:185], v[212:215], v[88:91]
	v_mfma_f32_16x16x32_bf16 v[76:79], v[174:177], v[238:241], v[76:79]
	v_mfma_f32_16x16x32_bf16 v[72:75], v[182:185], v[238:241], v[72:75]
	v_mfma_f32_16x16x32_bf16 v[126:129], v[178:181], v[200:203], v[126:129]
	v_mfma_f32_16x16x32_bf16 v[122:125], v[186:189], v[200:203], v[122:125]
	v_mfma_f32_16x16x32_bf16 v[108:111], v[178:181], v[208:211], v[108:111]
	v_mfma_f32_16x16x32_bf16 v[104:107], v[186:189], v[208:211], v[104:107]
	v_mfma_f32_16x16x32_bf16 v[92:95], v[178:181], v[234:237], v[92:95]
	v_mfma_f32_16x16x32_bf16 v[88:91], v[186:189], v[234:237], v[88:91]
	v_mfma_f32_16x16x32_bf16 v[76:79], v[178:181], v[242:245], v[76:79]
	v_mfma_f32_16x16x32_bf16 v[72:75], v[186:189], v[242:245], v[72:75]
	s_setprio 0
	s_barrier
	s_add_i32 s8, s13, s81
	s_add_u32 s100, s94, 0x80
	s_addc_u32 s101, s95, 0
	s_mov_b32 m0, s8
	ds_read_b128 v[190:193], v169 offset:49152
	ds_read_b128 v[200:203], v169 offset:50176
	ds_read_b128 v[204:207], v169 offset:51200
	ds_read_b128 v[208:211], v169 offset:52224
	ds_read_b128 v[212:215], v169 offset:53248
	ds_read_b128 v[234:237], v169 offset:54272
	ds_read_b128 v[238:241], v169 offset:55296
	ds_read_b128 v[242:245], v169 offset:56320
	global_load_lds_dwordx4 v112, s[100:101]
	s_add_i32 m0, s8, 0x2000
	s_add_u32 s8, s94, 0x40080
	v_lshl_add_u64 v[162:163], v[228:229], 0, s[24:25]
	s_addc_u32 s9, s95, 0
	s_add_i32 s13, s31, s81
	global_load_lds_dwordx4 v[162:163], off
	s_mov_b32 m0, s13
	s_nop 0
	global_load_lds_dwordx4 v112, s[8:9]
	s_add_i32 m0, s13, 0x2000
	s_nop 0
	global_load_lds_dwordx4 v142, s[8:9]
	s_add_u32 s100, vcc_lo, 0x80
	s_addc_u32 s101, vcc_hi, 0
	s_mov_b32 m0, s38
	s_nop 0
	global_load_lds_dwordx4 v138, s[100:101]
	s_add_u32 s100, vcc_lo, 0x80
	s_addc_u32 s101, vcc_hi, 0
	s_mov_b32 m0, s39
	s_nop 0
	global_load_lds_dwordx4 v140, s[100:101]
	s_waitcnt vmcnt(8)
	s_waitcnt lgkmcnt(0)
	s_barrier
	s_setprio 1
	s_waitcnt lgkmcnt(0)
	v_mfma_f32_16x16x32_bf16 v[68:71], v[150:153], v[190:193], v[68:71]
	v_mfma_f32_16x16x32_bf16 v[64:67], v[158:161], v[190:193], v[64:67]
	v_mfma_f32_16x16x32_bf16 v[52:55], v[150:153], v[204:207], v[52:55]
	v_mfma_f32_16x16x32_bf16 v[48:51], v[158:161], v[204:207], v[48:51]
	v_mfma_f32_16x16x32_bf16 v[36:39], v[150:153], v[212:215], v[36:39]
	v_mfma_f32_16x16x32_bf16 v[32:35], v[158:161], v[212:215], v[32:35]
	v_mfma_f32_16x16x32_bf16 v[20:23], v[150:153], v[238:241], v[20:23]
	v_mfma_f32_16x16x32_bf16 v[16:19], v[158:161], v[238:241], v[16:19]
	v_mfma_f32_16x16x32_bf16 v[68:71], v[154:157], v[200:203], v[68:71]
	v_mfma_f32_16x16x32_bf16 v[64:67], v[170:173], v[200:203], v[64:67]
	v_mfma_f32_16x16x32_bf16 v[52:55], v[154:157], v[208:211], v[52:55]
	v_mfma_f32_16x16x32_bf16 v[48:51], v[170:173], v[208:211], v[48:51]
	v_mfma_f32_16x16x32_bf16 v[36:39], v[154:157], v[234:237], v[36:39]
	v_mfma_f32_16x16x32_bf16 v[32:35], v[170:173], v[234:237], v[32:35]
	v_mfma_f32_16x16x32_bf16 v[20:23], v[154:157], v[242:245], v[20:23]
	v_mfma_f32_16x16x32_bf16 v[16:19], v[170:173], v[242:245], v[16:19]
	v_mfma_f32_16x16x32_bf16 v[60:63], v[174:177], v[190:193], v[60:63]
	v_mfma_f32_16x16x32_bf16 v[56:59], v[182:185], v[190:193], v[56:59]
	v_mfma_f32_16x16x32_bf16 v[44:47], v[174:177], v[204:207], v[44:47]
	v_mfma_f32_16x16x32_bf16 v[40:43], v[182:185], v[204:207], v[40:43]
	v_mfma_f32_16x16x32_bf16 v[28:31], v[174:177], v[212:215], v[28:31]
	v_mfma_f32_16x16x32_bf16 v[24:27], v[182:185], v[212:215], v[24:27]
	v_mfma_f32_16x16x32_bf16 v[12:15], v[174:177], v[238:241], v[12:15]
	v_mfma_f32_16x16x32_bf16 v[8:11], v[182:185], v[238:241], v[8:11]
	v_mfma_f32_16x16x32_bf16 v[60:63], v[178:181], v[200:203], v[60:63]
	v_mfma_f32_16x16x32_bf16 v[56:59], v[186:189], v[200:203], v[56:59]
	v_mfma_f32_16x16x32_bf16 v[44:47], v[178:181], v[208:211], v[44:47]
	v_mfma_f32_16x16x32_bf16 v[40:43], v[186:189], v[208:211], v[40:43]
	v_mfma_f32_16x16x32_bf16 v[28:31], v[178:181], v[234:237], v[28:31]
	v_mfma_f32_16x16x32_bf16 v[24:27], v[186:189], v[234:237], v[24:27]
	v_mfma_f32_16x16x32_bf16 v[12:15], v[178:181], v[242:245], v[12:15]
	v_mfma_f32_16x16x32_bf16 v[8:11], v[186:189], v[242:245], v[8:11]
	s_setprio 0
	s_barrier
	s_add_i32 s85, s85, 2
	s_add_u32 s40, s40, 0x100
	s_addc_u32 s41, s41, 0
	s_add_u32 s46, s46, 0x100
	s_addc_u32 s57, s57, 0
	s_cmp_gt_u32 s85, 13
	s_cbranch_scc0 .LBB0_268
	s_and_b64 vcc, exec, s[82:83]
	s_cbranch_vccz .LBB0_271
	s_barrier

; #define PG8_STAGE(bufoff, gbase, voff) do { _Pragma("unroll") for (int _i = 0; _i < 2; ++_i) \
;         __builtin_amdgcn_global_load_lds((const unsigned*)((const char*)(gbase) + (voff)[_i]), (LAS unsigned*)(lds + (bufoff) + ldsw + _i * 8192), 16, 0, 0); } while (0)
; #define PG8_LDA(dst, b, h) do { _Pragma("unroll") for (int m = 0; m < 4; ++m) _Pragma("unroll") for (int k = 0; k < 2; ++k) dst[m][k] = *(const LAS bf16x8*)(lds + PG8_SA(b, h) + aoff + m * 2048 + k * 1024); } while (0)
; #define PG8_LDB(dst, b, h) do { _Pragma("unroll") for (int n = 0; n < 2; ++n) _Pragma("unroll") for (int k = 0; k < 2; ++k) dst[n][k] = *(const LAS bf16x8*)(lds + PG8_SB(b, h) + boff + n * 2048 + k * 1024); } while (0)
; #define PG8_MMA(ai, bj, At, Bt) do { __builtin_amdgcn_s_setprio(1); _Pragma("unroll") for (int m = 0; m < 4; ++m) _Pragma("unroll") for (int n = 0; n < 2; ++n) _Pragma("unroll") for (int k = 0; k < 2; ++k) \
;         acc[ai][bj][m][n] = __builtin_amdgcn_mfma_f32_16x16x32_bf16(Bt[n][k], At[m][k], acc[ai][bj][m][n], 0, 0, 0); __builtin_amdgcn_s_setprio(0); } while (0)
; #define PG8_WAIT_V(n) asm volatile("s_waitcnt vmcnt(" #n ")" ::: "memory")
; #define PG8_WAIT_L(n) asm volatile("s_waitcnt lgkmcnt(" #n ")" ::: "memory")
; #define PG8_BAR __builtin_amdgcn_s_barrier()
; #define PG8_SCHED __builtin_amdgcn_sched_barrier(0)
; template <class Epi>
; __device__ __forceinline__ void gemm_phase(LAS unsigned char* lds, const Gemm g, const StaticOrder& S, const Epi& E, const int tid) {
;     ...
;             const char* a1 = cA + (size_t)(t + 1) * kstep + ((t + 1) >= 8 ? xtra : 0);
;             const char* a2 = last ? nA : cA + (size_t)(t + 2) * kstep + ((t + 2) >= 8 ? xtra : 0); const char* b2 = last ? nB : cB + (size_t)(t + 2) * kstep;
;             const char* a3 = a2 + kstep; const char* b3 = b2 + kstep;
;             PG8_LDB(B0, 0, 0); PG8_LDB(B1, 0, 1); PG8_SCHED; PG8_LDA(At, 0, 0); PG8_STAGE(PG8_SA(1, 1), a1 + hstepA, voffA);
;             PG8_WAIT_V(8); PG8_WAIT_L(0); PG8_BAR; PG8_MMA(0, 0, At, B0); PG8_MMA(0, 1, At, B1); PG8_BAR; PG8_SCHED;
;             PG8_LDA(At, 0, 1); PG8_STAGE(PG8_SB(0, 0), b2, voffB); PG8_STAGE(PG8_SB(0, 1), b2 + hstepB, voffB); PG8_STAGE(PG8_SA(0, 0), a2, voffA);
;             PG8_WAIT_V(8); PG8_WAIT_L(0); PG8_BAR; PG8_MMA(1, 0, At, B0); PG8_MMA(1, 1, At, B1); PG8_BAR; PG8_SCHED;
.LBB0_356:
	s_add_u32 s8, s42, 0xfffc0080
	s_addc_u32 s9, s43, -1
	s_add_i32 s13, 0, 0x10000
	v_add_u32_e32 v168, s13, v161
	v_add_u32_e32 v184, s15, v161
	ds_read_b128 v[150:153], v168
	ds_read_b128 v[154:157], v168 offset:1024
	ds_read_b128 v[164:167], v168 offset:2048
	ds_read_b128 v[168:171], v168 offset:3072
	ds_read_b128 v[172:175], v184
	ds_read_b128 v[176:179], v184 offset:1024
	ds_read_b128 v[180:183], v184 offset:2048
	ds_read_b128 v[184:187], v184 offset:3072
	s_cmp_eq_u32 s97, 12
	s_cselect_b32 s95, s98, s9
	s_cselect_b32 s94, s99, s8
	s_cselect_b32 s93, s83, s96
	s_cselect_b32 s92, vcc_lo, vcc_hi
	s_add_i32 m0, s19, 0xc000
	ds_read_b128 v[188:191], v163
	ds_read_b128 v[200:203], v163 offset:1024
	ds_read_b128 v[204:207], v163 offset:2048
	ds_read_b128 v[208:211], v163 offset:3072
	ds_read_b128 v[212:215], v163 offset:4096
	ds_read_b128 v[234:237], v163 offset:5120
	ds_read_b128 v[238:241], v163 offset:6144
	ds_read_b128 v[242:245], v163 offset:7168
	global_load_lds_dwordx4 v146, s[42:43]
	s_add_i32 m0, s19, 0xe000
	s_nop 0
	global_load_lds_dwordx4 v148, s[42:43]
	s_waitcnt vmcnt(8)
	s_waitcnt lgkmcnt(0)
	s_barrier
	s_setprio 1
	s_waitcnt lgkmcnt(0)
	v_mfma_f32_16x16x32_bf16 v[134:137], v[150:153], v[188:191], v[134:137]
	v_mfma_f32_16x16x32_bf16 v[130:133], v[164:167], v[188:191], v[130:133]
	v_mfma_f32_16x16x32_bf16 v[122:125], v[150:153], v[204:207], v[122:125]
	v_mfma_f32_16x16x32_bf16 v[114:117], v[164:167], v[204:207], v[114:117]
	v_mfma_f32_16x16x32_bf16 v[104:107], v[150:153], v[212:215], v[104:107]
	v_mfma_f32_16x16x32_bf16 v[96:99], v[164:167], v[212:215], v[96:99]
	v_mfma_f32_16x16x32_bf16 v[88:91], v[150:153], v[238:241], v[88:91]
	v_mfma_f32_16x16x32_bf16 v[80:83], v[164:167], v[238:241], v[80:83]
	v_mfma_f32_16x16x32_bf16 v[134:137], v[154:157], v[200:203], v[134:137]
	v_mfma_f32_16x16x32_bf16 v[130:133], v[168:171], v[200:203], v[130:133]
	v_mfma_f32_16x16x32_bf16 v[122:125], v[154:157], v[208:211], v[122:125]
	v_mfma_f32_16x16x32_bf16 v[114:117], v[168:171], v[208:211], v[114:117]
	v_mfma_f32_16x16x32_bf16 v[104:107], v[154:157], v[234:237], v[104:107]
	v_mfma_f32_16x16x32_bf16 v[96:99], v[168:171], v[234:237], v[96:99]
	v_mfma_f32_16x16x32_bf16 v[88:91], v[154:157], v[242:245], v[88:91]
	v_mfma_f32_16x16x32_bf16 v[80:83], v[168:171], v[242:245], v[80:83]
	v_mfma_f32_16x16x32_bf16 v[126:129], v[172:175], v[188:191], v[126:129]
	v_mfma_f32_16x16x32_bf16 v[118:121], v[180:183], v[188:191], v[118:121]
	v_mfma_f32_16x16x32_bf16 v[108:111], v[172:175], v[204:207], v[108:111]
	v_mfma_f32_16x16x32_bf16 v[100:103], v[180:183], v[204:207], v[100:103]
	v_mfma_f32_16x16x32_bf16 v[92:95], v[172:175], v[212:215], v[92:95]
	v_mfma_f32_16x16x32_bf16 v[84:87], v[180:183], v[212:215], v[84:87]
	v_mfma_f32_16x16x32_bf16 v[76:79], v[172:175], v[238:241], v[76:79]
	v_mfma_f32_16x16x32_bf16 v[72:75], v[180:183], v[238:241], v[72:75]
	v_mfma_f32_16x16x32_bf16 v[126:129], v[176:179], v[200:203], v[126:129]
	v_mfma_f32_16x16x32_bf16 v[118:121], v[184:187], v[200:203], v[118:121]
	v_mfma_f32_16x16x32_bf16 v[108:111], v[176:179], v[208:211], v[108:111]
	v_mfma_f32_16x16x32_bf16 v[100:103], v[184:187], v[208:211], v[100:103]
	v_mfma_f32_16x16x32_bf16 v[92:95], v[176:179], v[234:237], v[92:95]
	v_mfma_f32_16x16x32_bf16 v[84:87], v[184:187], v[234:237], v[84:87]
	v_mfma_f32_16x16x32_bf16 v[76:79], v[176:179], v[242:245], v[76:79]
	v_mfma_f32_16x16x32_bf16 v[72:75], v[184:187], v[242:245], v[72:75]
	s_setprio 0
	s_barrier
	s_add_i32 s8, s13, s17
	s_mov_b32 m0, s8
	ds_read_b128 v[188:191], v163 offset:16384
	ds_read_b128 v[200:203], v163 offset:17408
	ds_read_b128 v[204:207], v163 offset:18432
	ds_read_b128 v[208:211], v163 offset:19456
	ds_read_b128 v[212:215], v163 offset:20480
	ds_read_b128 v[234:237], v163 offset:21504
	ds_read_b128 v[238:241], v163 offset:22528
	ds_read_b128 v[242:245], v163 offset:23552
	global_load_lds_dwordx4 v112, s[92:93]
	s_add_i32 m0, s8, 0x2000
	s_add_u32 s8, s92, 0x40000
	v_lshl_add_u64 v[246:247], s[92:93], 0, v[142:143]
	s_addc_u32 s9, s93, 0
	s_add_i32 s13, s15, s17
	global_load_lds_dwordx4 v142, s[92:93]
	s_mov_b32 m0, s13
	s_nop 0
	global_load_lds_dwordx4 v112, s[8:9]
	s_add_i32 m0, s13, 0x2000
	s_nop 0
	global_load_lds_dwordx4 v142, s[8:9]
	s_mov_b32 m0, s19
	s_nop 0
	global_load_lds_dwordx4 v138, s[94:95]
	s_mov_b32 m0, s23
	s_nop 0
	global_load_lds_dwordx4 v140, s[94:95]
	s_waitcnt vmcnt(8)
	s_waitcnt lgkmcnt(0)
	s_barrier
	s_setprio 1
	s_waitcnt lgkmcnt(0)
	v_mfma_f32_16x16x32_bf16 v[68:71], v[150:153], v[188:191], v[68:71]
	v_mfma_f32_16x16x32_bf16 v[64:67], v[164:167], v[188:191], v[64:67]
	v_mfma_f32_16x16x32_bf16 v[56:59], v[150:153], v[204:207], v[56:59]
	v_mfma_f32_16x16x32_bf16 v[48:51], v[164:167], v[204:207], v[48:51]
	v_mfma_f32_16x16x32_bf16 v[40:43], v[150:153], v[212:215], v[40:43]
	v_mfma_f32_16x16x32_bf16 v[32:35], v[164:167], v[212:215], v[32:35]
	v_mfma_f32_16x16x32_bf16 v[24:27], v[150:153], v[238:241], v[24:27]
	v_mfma_f32_16x16x32_bf16 v[16:19], v[164:167], v[238:241], v[16:19]
	v_mfma_f32_16x16x32_bf16 v[68:71], v[154:157], v[200:203], v[68:71]
	v_mfma_f32_16x16x32_bf16 v[64:67], v[168:171], v[200:203], v[64:67]
	v_mfma_f32_16x16x32_bf16 v[56:59], v[154:157], v[208:211], v[56:59]
	v_mfma_f32_16x16x32_bf16 v[48:51], v[168:171], v[208:211], v[48:51]
	v_mfma_f32_16x16x32_bf16 v[40:43], v[154:157], v[234:237], v[40:43]
	v_mfma_f32_16x16x32_bf16 v[32:35], v[168:171], v[234:237], v[32:35]
	v_mfma_f32_16x16x32_bf16 v[24:27], v[154:157], v[242:245], v[24:27]
	v_mfma_f32_16x16x32_bf16 v[16:19], v[168:171], v[242:245], v[16:19]
	v_mfma_f32_16x16x32_bf16 v[60:63], v[172:175], v[188:191], v[60:63]
	v_mfma_f32_16x16x32_bf16 v[52:55], v[180:183], v[188:191], v[52:55]
	v_mfma_f32_16x16x32_bf16 v[44:47], v[172:175], v[204:207], v[44:47]
	v_mfma_f32_16x16x32_bf16 v[36:39], v[180:183], v[204:207], v[36:39]
	v_mfma_f32_16x16x32_bf16 v[28:31], v[172:175], v[212:215], v[28:31]
	v_mfma_f32_16x16x32_bf16 v[20:23], v[180:183], v[212:215], v[20:23]
	v_mfma_f32_16x16x32_bf16 v[12:15], v[172:175], v[238:241], v[12:15]
	v_mfma_f32_16x16x32_bf16 v[8:11], v[180:183], v[238:241], v[8:11]
	v_mfma_f32_16x16x32_bf16 v[60:63], v[176:179], v[200:203], v[60:63]
	v_mfma_f32_16x16x32_bf16 v[52:55], v[184:187], v[200:203], v[52:55]
	v_mfma_f32_16x16x32_bf16 v[44:47], v[176:179], v[208:211], v[44:47]
	v_mfma_f32_16x16x32_bf16 v[36:39], v[184:187], v[208:211], v[36:39]
	v_mfma_f32_16x16x32_bf16 v[28:31], v[176:179], v[234:237], v[28:31]
	v_mfma_f32_16x16x32_bf16 v[20:23], v[184:187], v[234:237], v[20:23]
	v_mfma_f32_16x16x32_bf16 v[12:15], v[176:179], v[242:245], v[12:15]
	v_mfma_f32_16x16x32_bf16 v[8:11], v[184:187], v[242:245], v[8:11]
	s_setprio 0
	s_barrier
; #define PG8_STAGE(bufoff, gbase, voff) do { _Pragma("unroll") for (int _i = 0; _i < 2; ++_i) \
;         __builtin_amdgcn_global_load_lds((const unsigned*)((const char*)(gbase) + (voff)[_i]), (LAS unsigned*)(lds + (bufoff) + ldsw + _i * 8192), 16, 0, 0); } while (0)
; #define PG8_LDA(dst, b, h) do { _Pragma("unroll") for (int m = 0; m < 4; ++m) _Pragma("unroll") for (int k = 0; k < 2; ++k) dst[m][k] = *(const LAS bf16x8*)(lds + PG8_SA(b, h) + aoff + m * 2048 + k * 1024); } while (0)
; #define PG8_LDB(dst, b, h) do { _Pragma("unroll") for (int n = 0; n < 2; ++n) _Pragma("unroll") for (int k = 0; k < 2; ++k) dst[n][k] = *(const LAS bf16x8*)(lds + PG8_SB(b, h) + boff + n * 2048 + k * 1024); } while (0)
; #define PG8_MMA(ai, bj, At, Bt) do { __builtin_amdgcn_s_setprio(1); _Pragma("unroll") for (int m = 0; m < 4; ++m) _Pragma("unroll") for (int n = 0; n < 2; ++n) _Pragma("unroll") for (int k = 0; k < 2; ++k) \
;         acc[ai][bj][m][n] = __builtin_amdgcn_mfma_f32_16x16x32_bf16(Bt[n][k], At[m][k], acc[ai][bj][m][n], 0, 0, 0); __builtin_amdgcn_s_setprio(0); } while (0)
; #define PG8_WAIT_V(n) asm volatile("s_waitcnt vmcnt(" #n ")" ::: "memory")
; #define PG8_WAIT_L(n) asm volatile("s_waitcnt lgkmcnt(" #n ")" ::: "memory")
; #define PG8_BAR __builtin_amdgcn_s_barrier()
; #define PG8_SCHED __builtin_amdgcn_sched_barrier(0)
; template <class Epi>
; __device__ __forceinline__ void gemm_phase(LAS unsigned char* lds, const Gemm g, const StaticOrder& S, const Epi& E, const int tid) {
;     ...
;             PG8_LDB(B0, 1, 0); PG8_LDB(B1, 1, 1); PG8_SCHED; PG8_LDA(At, 1, 0); PG8_STAGE(PG8_SA(0, 1), a2 + hstepA, voffA);
;             PG8_WAIT_V(8); PG8_WAIT_L(0); PG8_BAR; PG8_MMA(0, 0, At, B0); PG8_MMA(0, 1, At, B1); PG8_BAR; PG8_SCHED;
;             PG8_LDA(At, 1, 1); PG8_STAGE(PG8_SB(1, 0), b3, voffB); PG8_STAGE(PG8_SB(1, 1), b3 + hstepB, voffB); PG8_STAGE(PG8_SA(1, 0), a3, voffA);
;             PG8_WAIT_V(8); PG8_WAIT_L(0); PG8_BAR; PG8_MMA(1, 0, At, B0); PG8_MMA(1, 1, At, B1); PG8_BAR; PG8_SCHED;
;         }
;         if (wr == 0) PG8_BAR;
	s_add_i32 s13, 0, 0x18000
	s_add_i32 s31, 0, 0x1c000
	v_add_u32_e32 v168, s13, v161
	v_add_u32_e32 v184, s31, v161
	ds_read_b128 v[150:153], v168
	ds_read_b128 v[154:157], v168 offset:1024
	ds_read_b128 v[164:167], v168 offset:2048
	ds_read_b128 v[168:171], v168 offset:3072
	ds_read_b128 v[172:175], v184
	ds_read_b128 v[176:179], v184 offset:1024
	ds_read_b128 v[180:183], v184 offset:2048
	ds_read_b128 v[184:187], v184 offset:3072
	s_add_u32 s8, s94, 0x40000
	s_addc_u32 s9, s95, 0
	s_mov_b32 m0, s28
	ds_read_b128 v[188:191], v163 offset:32768
	ds_read_b128 v[200:203], v163 offset:33792
	ds_read_b128 v[204:207], v163 offset:34816
	ds_read_b128 v[208:211], v163 offset:35840
	ds_read_b128 v[212:215], v163 offset:36864
	ds_read_b128 v[234:237], v163 offset:37888
	ds_read_b128 v[238:241], v163 offset:38912
	ds_read_b128 v[242:245], v163 offset:39936
	global_load_lds_dwordx4 v138, s[8:9]
	s_mov_b32 m0, s30
	s_nop 0
	global_load_lds_dwordx4 v140, s[8:9]
	s_waitcnt vmcnt(8)
	s_waitcnt lgkmcnt(0)
	s_barrier
	s_setprio 1
	s_waitcnt lgkmcnt(0)
	v_mfma_f32_16x16x32_bf16 v[134:137], v[150:153], v[188:191], v[134:137]
	v_mfma_f32_16x16x32_bf16 v[130:133], v[164:167], v[188:191], v[130:133]
	v_mfma_f32_16x16x32_bf16 v[122:125], v[150:153], v[204:207], v[122:125]
	v_mfma_f32_16x16x32_bf16 v[114:117], v[164:167], v[204:207], v[114:117]
	v_mfma_f32_16x16x32_bf16 v[104:107], v[150:153], v[212:215], v[104:107]
	v_mfma_f32_16x16x32_bf16 v[96:99], v[164:167], v[212:215], v[96:99]
	v_mfma_f32_16x16x32_bf16 v[88:91], v[150:153], v[238:241], v[88:91]
	v_mfma_f32_16x16x32_bf16 v[80:83], v[164:167], v[238:241], v[80:83]
	v_mfma_f32_16x16x32_bf16 v[134:137], v[154:157], v[200:203], v[134:137]
	v_mfma_f32_16x16x32_bf16 v[130:133], v[168:171], v[200:203], v[130:133]
	v_mfma_f32_16x16x32_bf16 v[122:125], v[154:157], v[208:211], v[122:125]
	v_mfma_f32_16x16x32_bf16 v[114:117], v[168:171], v[208:211], v[114:117]
	v_mfma_f32_16x16x32_bf16 v[104:107], v[154:157], v[234:237], v[104:107]
	v_mfma_f32_16x16x32_bf16 v[96:99], v[168:171], v[234:237], v[96:99]
	v_mfma_f32_16x16x32_bf16 v[88:91], v[154:157], v[242:245], v[88:91]
	v_mfma_f32_16x16x32_bf16 v[80:83], v[168:171], v[242:245], v[80:83]
	v_mfma_f32_16x16x32_bf16 v[126:129], v[172:175], v[188:191], v[126:129]
	v_mfma_f32_16x16x32_bf16 v[118:121], v[180:183], v[188:191], v[118:121]
	v_mfma_f32_16x16x32_bf16 v[108:111], v[172:175], v[204:207], v[108:111]
	v_mfma_f32_16x16x32_bf16 v[100:103], v[180:183], v[204:207], v[100:103]
	v_mfma_f32_16x16x32_bf16 v[92:95], v[172:175], v[212:215], v[92:95]
	v_mfma_f32_16x16x32_bf16 v[84:87], v[180:183], v[212:215], v[84:87]
	v_mfma_f32_16x16x32_bf16 v[76:79], v[172:175], v[238:241], v[76:79]
	v_mfma_f32_16x16x32_bf16 v[72:75], v[180:183], v[238:241], v[72:75]
	v_mfma_f32_16x16x32_bf16 v[126:129], v[176:179], v[200:203], v[126:129]
	v_mfma_f32_16x16x32_bf16 v[118:121], v[184:187], v[200:203], v[118:121]
	v_mfma_f32_16x16x32_bf16 v[108:111], v[176:179], v[208:211], v[108:111]
	v_mfma_f32_16x16x32_bf16 v[100:103], v[184:187], v[208:211], v[100:103]
	v_mfma_f32_16x16x32_bf16 v[92:95], v[176:179], v[234:237], v[92:95]
	v_mfma_f32_16x16x32_bf16 v[84:87], v[184:187], v[234:237], v[84:87]
	v_mfma_f32_16x16x32_bf16 v[76:79], v[176:179], v[242:245], v[76:79]
	v_mfma_f32_16x16x32_bf16 v[72:75], v[184:187], v[242:245], v[72:75]
	s_setprio 0
	s_barrier
	s_add_i32 s8, s13, s17
	s_add_u32 s100, s92, 0x80
	s_addc_u32 s101, s93, 0
	s_mov_b32 m0, s8
	ds_read_b128 v[188:191], v163 offset:49152
	ds_read_b128 v[200:203], v163 offset:50176
	ds_read_b128 v[204:207], v163 offset:51200
	ds_read_b128 v[208:211], v163 offset:52224
	ds_read_b128 v[212:215], v163 offset:53248
	ds_read_b128 v[234:237], v163 offset:54272
	ds_read_b128 v[238:241], v163 offset:55296
	ds_read_b128 v[242:245], v163 offset:56320
	global_load_lds_dwordx4 v112, s[100:101]
	s_add_i32 m0, s8, 0x2000
	s_add_u32 s8, s92, 0x40080
	v_lshl_add_u64 v[192:193], v[246:247], 0, s[24:25]
	s_addc_u32 s9, s93, 0
	s_add_i32 s13, s31, s17
	global_load_lds_dwordx4 v[192:193], off
	s_mov_b32 m0, s13
	s_nop 0
	global_load_lds_dwordx4 v112, s[8:9]
	s_add_i32 m0, s13, 0x2000
	s_nop 0
	global_load_lds_dwordx4 v142, s[8:9]
	s_add_u32 s100, s94, 0x80
	s_addc_u32 s101, s95, 0
	s_mov_b32 m0, s36
	s_nop 0
	global_load_lds_dwordx4 v138, s[100:101]
	s_add_u32 s100, s94, 0x80
	s_addc_u32 s101, s95, 0
	s_mov_b32 m0, s37
	s_nop 0
	global_load_lds_dwordx4 v140, s[100:101]
	s_waitcnt vmcnt(8)
	s_waitcnt lgkmcnt(0)
	s_barrier
	s_setprio 1
	s_waitcnt lgkmcnt(0)
	v_mfma_f32_16x16x32_bf16 v[68:71], v[150:153], v[188:191], v[68:71]
	v_mfma_f32_16x16x32_bf16 v[64:67], v[164:167], v[188:191], v[64:67]
	v_mfma_f32_16x16x32_bf16 v[56:59], v[150:153], v[204:207], v[56:59]
	v_mfma_f32_16x16x32_bf16 v[48:51], v[164:167], v[204:207], v[48:51]
	v_mfma_f32_16x16x32_bf16 v[40:43], v[150:153], v[212:215], v[40:43]
	v_mfma_f32_16x16x32_bf16 v[32:35], v[164:167], v[212:215], v[32:35]
	v_mfma_f32_16x16x32_bf16 v[24:27], v[150:153], v[238:241], v[24:27]
	v_mfma_f32_16x16x32_bf16 v[16:19], v[164:167], v[238:241], v[16:19]
	v_mfma_f32_16x16x32_bf16 v[68:71], v[154:157], v[200:203], v[68:71]
	v_mfma_f32_16x16x32_bf16 v[64:67], v[168:171], v[200:203], v[64:67]
	v_mfma_f32_16x16x32_bf16 v[56:59], v[154:157], v[208:211], v[56:59]
	v_mfma_f32_16x16x32_bf16 v[48:51], v[168:171], v[208:211], v[48:51]
	v_mfma_f32_16x16x32_bf16 v[40:43], v[154:157], v[234:237], v[40:43]
	v_mfma_f32_16x16x32_bf16 v[32:35], v[168:171], v[234:237], v[32:35]
	v_mfma_f32_16x16x32_bf16 v[24:27], v[154:157], v[242:245], v[24:27]
	v_mfma_f32_16x16x32_bf16 v[16:19], v[168:171], v[242:245], v[16:19]
	v_mfma_f32_16x16x32_bf16 v[60:63], v[172:175], v[188:191], v[60:63]
	v_mfma_f32_16x16x32_bf16 v[52:55], v[180:183], v[188:191], v[52:55]
	v_mfma_f32_16x16x32_bf16 v[44:47], v[172:175], v[204:207], v[44:47]
	v_mfma_f32_16x16x32_bf16 v[36:39], v[180:183], v[204:207], v[36:39]
	v_mfma_f32_16x16x32_bf16 v[28:31], v[172:175], v[212:215], v[28:31]
	v_mfma_f32_16x16x32_bf16 v[20:23], v[180:183], v[212:215], v[20:23]
	v_mfma_f32_16x16x32_bf16 v[12:15], v[172:175], v[238:241], v[12:15]
	v_mfma_f32_16x16x32_bf16 v[8:11], v[180:183], v[238:241], v[8:11]
	v_mfma_f32_16x16x32_bf16 v[60:63], v[176:179], v[200:203], v[60:63]
	v_mfma_f32_16x16x32_bf16 v[52:55], v[184:187], v[200:203], v[52:55]
	v_mfma_f32_16x16x32_bf16 v[44:47], v[176:179], v[208:211], v[44:47]
	v_mfma_f32_16x16x32_bf16 v[36:39], v[184:187], v[208:211], v[36:39]
	v_mfma_f32_16x16x32_bf16 v[28:31], v[176:179], v[234:237], v[28:31]
	v_mfma_f32_16x16x32_bf16 v[20:23], v[184:187], v[234:237], v[20:23]
	v_mfma_f32_16x16x32_bf16 v[12:15], v[176:179], v[242:245], v[12:15]
	v_mfma_f32_16x16x32_bf16 v[8:11], v[184:187], v[242:245], v[8:11]
	s_setprio 0
	s_barrier
	s_add_i32 s97, s97, 2
	s_add_u32 s42, s42, 0x100
	s_addc_u32 s43, s43, 0
	s_add_u32 vcc_hi, vcc_hi, 0x100
	s_addc_u32 s96, s96, 0
	s_cmp_gt_u32 s97, 13
	s_cbranch_scc0 .LBB0_356
	s_and_b64 vcc, exec, s[80:81]
	s_cbranch_vccz .LBB0_359
	s_barrier
